# GEMM K-loops: all s_setprio toggles around the MFMA blocks removed (chained A-row-major order kept)
# speedup vs baseline: 1.0100x; 1.0065x over previous
.LBB0_260:
	v_add_u32_e32 v168, 0x10000, v232
	v_add_u32_e32 v180, 0x14000, v232
	v_lshl_add_u64 v[224:225], v[222:223], 0, s[62:63]
	s_add_i32 m0, s35, 0xc000
	s_waitcnt lgkmcnt(0)
	ds_read_b128 v[148:151], v207
	ds_read_b128 v[164:167], v207 offset:1024
	ds_read_b128 v[144:147], v207 offset:2048
	ds_read_b128 v[160:163], v207 offset:3072
	ds_read_b128 v[140:143], v207 offset:4096
	ds_read_b128 v[156:159], v207 offset:5120
	ds_read_b128 v[136:139], v207 offset:6144
	ds_read_b128 v[152:155], v207 offset:7168
	ds_read_b128 v[184:187], v168
	ds_read_b128 v[188:191], v168 offset:1024
	ds_read_b128 v[192:195], v168 offset:2048
	ds_read_b128 v[196:199], v168 offset:3072
	ds_read_b128 v[168:171], v180
	ds_read_b128 v[172:175], v180 offset:1024
	ds_read_b128 v[176:179], v180 offset:2048
	ds_read_b128 v[180:183], v180 offset:3072
	global_load_lds_dwordx4 v[224:225], off
	v_lshl_add_u64 v[224:225], v[220:221], 0, s[62:63]
	s_add_i32 m0, s35, 0xe000
	s_nop 0
	global_load_lds_dwordx4 v[224:225], off
	s_waitcnt vmcnt(8)
	s_waitcnt lgkmcnt(0)
	s_barrier
	s_waitcnt lgkmcnt(0)
	v_mfma_f32_16x16x32_bf16 v[132:135], v[184:187], v[148:151], v[132:135]
	v_mfma_f32_16x16x32_bf16 v[132:135], v[188:191], v[164:167], v[132:135]
	v_mfma_f32_16x16x32_bf16 v[128:131], v[192:195], v[148:151], v[128:131]
	v_mfma_f32_16x16x32_bf16 v[128:131], v[196:199], v[164:167], v[128:131]
	v_mfma_f32_16x16x32_bf16 v[124:127], v[168:171], v[148:151], v[124:127]
	v_mfma_f32_16x16x32_bf16 v[124:127], v[172:175], v[164:167], v[124:127]
	v_mfma_f32_16x16x32_bf16 v[120:123], v[176:179], v[148:151], v[120:123]
	v_mfma_f32_16x16x32_bf16 v[120:123], v[180:183], v[164:167], v[120:123]
	v_mfma_f32_16x16x32_bf16 v[116:119], v[184:187], v[144:147], v[116:119]
	v_mfma_f32_16x16x32_bf16 v[116:119], v[188:191], v[160:163], v[116:119]
	v_mfma_f32_16x16x32_bf16 v[112:115], v[192:195], v[144:147], v[112:115]
	v_mfma_f32_16x16x32_bf16 v[112:115], v[196:199], v[160:163], v[112:115]
	v_mfma_f32_16x16x32_bf16 v[108:111], v[168:171], v[144:147], v[108:111]
	v_mfma_f32_16x16x32_bf16 v[108:111], v[172:175], v[160:163], v[108:111]
	v_mfma_f32_16x16x32_bf16 v[104:107], v[176:179], v[144:147], v[104:107]
	v_mfma_f32_16x16x32_bf16 v[104:107], v[180:183], v[160:163], v[104:107]
	v_mfma_f32_16x16x32_bf16 v[100:103], v[184:187], v[140:143], v[100:103]
	v_mfma_f32_16x16x32_bf16 v[100:103], v[188:191], v[156:159], v[100:103]
	v_mfma_f32_16x16x32_bf16 v[96:99], v[192:195], v[140:143], v[96:99]
	v_mfma_f32_16x16x32_bf16 v[96:99], v[196:199], v[156:159], v[96:99]
	v_mfma_f32_16x16x32_bf16 v[92:95], v[168:171], v[140:143], v[92:95]
	v_mfma_f32_16x16x32_bf16 v[92:95], v[172:175], v[156:159], v[92:95]
	v_mfma_f32_16x16x32_bf16 v[88:91], v[176:179], v[140:143], v[88:91]
	v_mfma_f32_16x16x32_bf16 v[88:91], v[180:183], v[156:159], v[88:91]
	v_mfma_f32_16x16x32_bf16 v[84:87], v[184:187], v[136:139], v[84:87]
	v_mfma_f32_16x16x32_bf16 v[84:87], v[188:191], v[152:155], v[84:87]
	v_mfma_f32_16x16x32_bf16 v[80:83], v[192:195], v[136:139], v[80:83]
	v_mfma_f32_16x16x32_bf16 v[80:83], v[196:199], v[152:155], v[80:83]
	v_mfma_f32_16x16x32_bf16 v[76:79], v[168:171], v[136:139], v[76:79]
	v_mfma_f32_16x16x32_bf16 v[76:79], v[172:175], v[152:155], v[76:79]
	v_mfma_f32_16x16x32_bf16 v[72:75], v[176:179], v[136:139], v[72:75]
	v_mfma_f32_16x16x32_bf16 v[72:75], v[180:183], v[152:155], v[72:75]
	s_barrier
	v_cndmask_b32_e64 v204, 0, 1, s[60:61]
	v_cmp_ne_u32_e64 s[50:51], 1, v204
	s_andn2_b64 vcc, exec, s[60:61]
	s_cbranch_vccnz .LBB0_262
	ds_read_b128 v[148:151], v207 offset:16384
	ds_read_b128 v[164:167], v207 offset:17408
	ds_read_b128 v[144:147], v207 offset:18432
	ds_read_b128 v[160:163], v207 offset:19456
	ds_read_b128 v[140:143], v207 offset:20480
	ds_read_b128 v[156:159], v207 offset:21504
	ds_read_b128 v[136:139], v207 offset:22528
	ds_read_b128 v[152:155], v207 offset:23552
.LBB0_262:
	s_add_u32 s12, s58, s62
	s_addc_u32 s13, s59, s63
	s_add_u32 s14, s12, 0x100
	s_addc_u32 s15, s13, 0
	s_add_u32 s75, s26, s62
	s_addc_u32 s76, s27, s63
	s_cmpk_eq_i32 s62, 0xf00
	s_cselect_b64 s[52:53], -1, 0
	s_and_b64 s[12:13], s[52:53], exec
	s_cselect_b32 s13, s21, s76
	s_cselect_b32 s12, s73, s75
	s_mov_b32 m0, s38
	s_cselect_b32 s15, s25, s15
	s_cselect_b32 s14, s33, s14
	v_lshl_add_u64 v[224:225], s[12:13], 0, v[208:209]
	s_add_u32 s76, s12, 0x80000
	global_load_lds_dwordx4 v[224:225], off
	v_lshl_add_u64 v[226:227], s[12:13], 0, v[212:213]
	s_mov_b32 m0, s39
	s_addc_u32 s77, s13, 0
	global_load_lds_dwordx4 v[226:227], off
	v_lshl_add_u64 v[228:229], s[76:77], 0, v[208:209]
	s_mov_b32 m0, s40
	v_lshl_add_u64 v[230:231], s[14:15], 0, v[210:211]
	global_load_lds_dwordx4 v[228:229], off
	v_lshl_add_u64 v[228:229], s[76:77], 0, v[212:213]
	s_mov_b32 m0, s41
	s_and_b64 vcc, exec, s[50:51]
	global_load_lds_dwordx4 v[228:229], off
	v_lshl_add_u64 v[228:229], s[14:15], 0, v[4:5]
	s_mov_b32 m0, s35
	s_nop 0
	global_load_lds_dwordx4 v[228:229], off
	s_mov_b32 m0, s43
	s_nop 0
	global_load_lds_dwordx4 v[230:231], off
	s_waitcnt vmcnt(8)
	s_waitcnt lgkmcnt(0)
	s_barrier
	s_cbranch_vccnz .LBB0_264
	s_waitcnt lgkmcnt(0)
	v_mfma_f32_16x16x32_bf16 v[68:71], v[184:187], v[148:151], v[68:71]
	v_mfma_f32_16x16x32_bf16 v[68:71], v[188:191], v[164:167], v[68:71]
	v_mfma_f32_16x16x32_bf16 v[64:67], v[192:195], v[148:151], v[64:67]
	v_mfma_f32_16x16x32_bf16 v[64:67], v[196:199], v[164:167], v[64:67]
	v_mfma_f32_16x16x32_bf16 v[60:63], v[168:171], v[148:151], v[60:63]
	v_mfma_f32_16x16x32_bf16 v[60:63], v[172:175], v[164:167], v[60:63]
	v_mfma_f32_16x16x32_bf16 v[56:59], v[176:179], v[148:151], v[56:59]
	v_mfma_f32_16x16x32_bf16 v[56:59], v[180:183], v[164:167], v[56:59]
	v_mfma_f32_16x16x32_bf16 v[52:55], v[184:187], v[144:147], v[52:55]
	v_mfma_f32_16x16x32_bf16 v[52:55], v[188:191], v[160:163], v[52:55]
	v_mfma_f32_16x16x32_bf16 v[48:51], v[192:195], v[144:147], v[48:51]
	v_mfma_f32_16x16x32_bf16 v[48:51], v[196:199], v[160:163], v[48:51]
	v_mfma_f32_16x16x32_bf16 v[44:47], v[168:171], v[144:147], v[44:47]
	v_mfma_f32_16x16x32_bf16 v[44:47], v[172:175], v[160:163], v[44:47]
	v_mfma_f32_16x16x32_bf16 v[40:43], v[176:179], v[144:147], v[40:43]
	v_mfma_f32_16x16x32_bf16 v[40:43], v[180:183], v[160:163], v[40:43]
	v_mfma_f32_16x16x32_bf16 v[36:39], v[184:187], v[140:143], v[36:39]
	v_mfma_f32_16x16x32_bf16 v[36:39], v[188:191], v[156:159], v[36:39]
	v_mfma_f32_16x16x32_bf16 v[32:35], v[192:195], v[140:143], v[32:35]
	v_mfma_f32_16x16x32_bf16 v[32:35], v[196:199], v[156:159], v[32:35]
	v_mfma_f32_16x16x32_bf16 v[28:31], v[168:171], v[140:143], v[28:31]
	v_mfma_f32_16x16x32_bf16 v[28:31], v[172:175], v[156:159], v[28:31]
	v_mfma_f32_16x16x32_bf16 v[24:27], v[176:179], v[140:143], v[24:27]
	v_mfma_f32_16x16x32_bf16 v[24:27], v[180:183], v[156:159], v[24:27]
	v_mfma_f32_16x16x32_bf16 v[20:23], v[184:187], v[136:139], v[20:23]
	v_mfma_f32_16x16x32_bf16 v[20:23], v[188:191], v[152:155], v[20:23]
	v_mfma_f32_16x16x32_bf16 v[16:19], v[192:195], v[136:139], v[16:19]
	v_mfma_f32_16x16x32_bf16 v[16:19], v[196:199], v[152:155], v[16:19]
	v_mfma_f32_16x16x32_bf16 v[12:15], v[168:171], v[136:139], v[12:15]
	v_mfma_f32_16x16x32_bf16 v[12:15], v[172:175], v[152:155], v[12:15]
	v_mfma_f32_16x16x32_bf16 v[8:11], v[176:179], v[136:139], v[8:11]
	v_mfma_f32_16x16x32_bf16 v[8:11], v[180:183], v[152:155], v[8:11]
.LBB0_264:
	s_barrier
	v_cndmask_b32_e64 v241, v219, 0, s[52:53]
	v_cndmask_b32_e64 v240, v218, v2, s[52:53]
	v_lshl_add_u64 v[240:241], s[14:15], 0, v[240:241]
	s_mov_b32 m0, s45
	v_add_u32_e32 v168, 0x18000, v232
	v_add_u32_e32 v180, 0x1c000, v232
	v_lshl_add_u64 v[242:243], v[240:241], 0, v[4:5]
	s_waitcnt lgkmcnt(0)
	ds_read_b128 v[148:151], v207 offset:32768
	ds_read_b128 v[164:167], v207 offset:33792
	ds_read_b128 v[144:147], v207 offset:34816
	ds_read_b128 v[160:163], v207 offset:35840
	ds_read_b128 v[140:143], v207 offset:36864
	ds_read_b128 v[156:159], v207 offset:37888
	ds_read_b128 v[136:139], v207 offset:38912
	ds_read_b128 v[152:155], v207 offset:39936
	ds_read_b128 v[184:187], v168
	ds_read_b128 v[188:191], v168 offset:1024
	ds_read_b128 v[192:195], v168 offset:2048
	ds_read_b128 v[196:199], v168 offset:3072
	ds_read_b128 v[168:171], v180
	ds_read_b128 v[172:175], v180 offset:1024
	ds_read_b128 v[176:179], v180 offset:2048
	ds_read_b128 v[180:183], v180 offset:3072
	global_load_lds_dwordx4 v[242:243], off
	v_lshl_add_u64 v[240:241], v[240:241], 0, v[210:211]
	s_mov_b32 m0, s47
	s_nop 0
	global_load_lds_dwordx4 v[240:241], off
	s_waitcnt vmcnt(8)
	s_waitcnt lgkmcnt(0)
	s_barrier
	s_waitcnt lgkmcnt(0)
	v_mfma_f32_16x16x32_bf16 v[132:135], v[184:187], v[148:151], v[132:135]
	v_mfma_f32_16x16x32_bf16 v[132:135], v[188:191], v[164:167], v[132:135]
	v_mfma_f32_16x16x32_bf16 v[128:131], v[192:195], v[148:151], v[128:131]
	v_mfma_f32_16x16x32_bf16 v[128:131], v[196:199], v[164:167], v[128:131]
	v_mfma_f32_16x16x32_bf16 v[124:127], v[168:171], v[148:151], v[124:127]
	v_mfma_f32_16x16x32_bf16 v[124:127], v[172:175], v[164:167], v[124:127]
	v_mfma_f32_16x16x32_bf16 v[120:123], v[176:179], v[148:151], v[120:123]
	v_mfma_f32_16x16x32_bf16 v[120:123], v[180:183], v[164:167], v[120:123]
	v_mfma_f32_16x16x32_bf16 v[116:119], v[184:187], v[144:147], v[116:119]
	v_mfma_f32_16x16x32_bf16 v[116:119], v[188:191], v[160:163], v[116:119]
	v_mfma_f32_16x16x32_bf16 v[112:115], v[192:195], v[144:147], v[112:115]
	v_mfma_f32_16x16x32_bf16 v[112:115], v[196:199], v[160:163], v[112:115]
	v_mfma_f32_16x16x32_bf16 v[108:111], v[168:171], v[144:147], v[108:111]
	v_mfma_f32_16x16x32_bf16 v[108:111], v[172:175], v[160:163], v[108:111]
	v_mfma_f32_16x16x32_bf16 v[104:107], v[176:179], v[144:147], v[104:107]
	v_mfma_f32_16x16x32_bf16 v[104:107], v[180:183], v[160:163], v[104:107]
	v_mfma_f32_16x16x32_bf16 v[100:103], v[184:187], v[140:143], v[100:103]
	v_mfma_f32_16x16x32_bf16 v[100:103], v[188:191], v[156:159], v[100:103]
	v_mfma_f32_16x16x32_bf16 v[96:99], v[192:195], v[140:143], v[96:99]
	v_mfma_f32_16x16x32_bf16 v[96:99], v[196:199], v[156:159], v[96:99]
	v_mfma_f32_16x16x32_bf16 v[92:95], v[168:171], v[140:143], v[92:95]
	v_mfma_f32_16x16x32_bf16 v[92:95], v[172:175], v[156:159], v[92:95]
	v_mfma_f32_16x16x32_bf16 v[88:91], v[176:179], v[140:143], v[88:91]
	v_mfma_f32_16x16x32_bf16 v[88:91], v[180:183], v[156:159], v[88:91]
	v_mfma_f32_16x16x32_bf16 v[84:87], v[184:187], v[136:139], v[84:87]
	v_mfma_f32_16x16x32_bf16 v[84:87], v[188:191], v[152:155], v[84:87]
	v_mfma_f32_16x16x32_bf16 v[80:83], v[192:195], v[136:139], v[80:83]
	v_mfma_f32_16x16x32_bf16 v[80:83], v[196:199], v[152:155], v[80:83]
	v_mfma_f32_16x16x32_bf16 v[76:79], v[168:171], v[136:139], v[76:79]
	v_mfma_f32_16x16x32_bf16 v[76:79], v[172:175], v[152:155], v[76:79]
	v_mfma_f32_16x16x32_bf16 v[72:75], v[176:179], v[136:139], v[72:75]
	v_mfma_f32_16x16x32_bf16 v[72:75], v[180:183], v[152:155], v[72:75]
	s_barrier
	s_and_b64 vcc, exec, s[50:51]
	s_cbranch_vccnz .LBB0_266
	ds_read_b128 v[148:151], v207 offset:49152
	ds_read_b128 v[164:167], v207 offset:50176
	ds_read_b128 v[144:147], v207 offset:51200
	ds_read_b128 v[160:163], v207 offset:52224
	ds_read_b128 v[140:143], v207 offset:53248
	ds_read_b128 v[156:159], v207 offset:54272
	ds_read_b128 v[136:139], v207 offset:55296
	ds_read_b128 v[152:155], v207 offset:56320
.LBB0_266:
	s_mov_b32 m0, s64
	v_lshl_add_u64 v[224:225], v[224:225], 0, s[0:1]
	s_add_u32 s12, s12, 0x80080
	global_load_lds_dwordx4 v[224:225], off
	v_lshl_add_u64 v[224:225], v[226:227], 0, s[0:1]
	s_mov_b32 m0, s65
	s_addc_u32 s13, s13, 0
	global_load_lds_dwordx4 v[224:225], off
	v_lshl_add_u64 v[224:225], s[12:13], 0, v[208:209]
	s_mov_b32 m0, s68
	s_and_b64 vcc, exec, s[50:51]
	global_load_lds_dwordx4 v[224:225], off
	v_lshl_add_u64 v[224:225], s[12:13], 0, v[212:213]
	s_mov_b32 m0, s69
	s_nop 0
	global_load_lds_dwordx4 v[224:225], off
	v_lshl_add_u64 v[224:225], v[228:229], 0, s[0:1]
	s_mov_b32 m0, s66
	s_nop 0
	global_load_lds_dwordx4 v[224:225], off
	v_lshl_add_u64 v[224:225], v[230:231], 0, s[0:1]
	s_mov_b32 m0, s67
	s_nop 0
	global_load_lds_dwordx4 v[224:225], off
	s_waitcnt vmcnt(8)
	s_waitcnt lgkmcnt(0)
	s_barrier
	s_cbranch_vccnz .LBB0_259
	s_waitcnt lgkmcnt(0)
	v_mfma_f32_16x16x32_bf16 v[68:71], v[184:187], v[148:151], v[68:71]
	v_mfma_f32_16x16x32_bf16 v[68:71], v[188:191], v[164:167], v[68:71]
	v_mfma_f32_16x16x32_bf16 v[64:67], v[192:195], v[148:151], v[64:67]
	v_mfma_f32_16x16x32_bf16 v[64:67], v[196:199], v[164:167], v[64:67]
	v_mfma_f32_16x16x32_bf16 v[60:63], v[168:171], v[148:151], v[60:63]
	v_mfma_f32_16x16x32_bf16 v[60:63], v[172:175], v[164:167], v[60:63]
	v_mfma_f32_16x16x32_bf16 v[56:59], v[176:179], v[148:151], v[56:59]
	v_mfma_f32_16x16x32_bf16 v[56:59], v[180:183], v[164:167], v[56:59]
	v_mfma_f32_16x16x32_bf16 v[52:55], v[184:187], v[144:147], v[52:55]
	v_mfma_f32_16x16x32_bf16 v[52:55], v[188:191], v[160:163], v[52:55]
	v_mfma_f32_16x16x32_bf16 v[48:51], v[192:195], v[144:147], v[48:51]
	v_mfma_f32_16x16x32_bf16 v[48:51], v[196:199], v[160:163], v[48:51]
	v_mfma_f32_16x16x32_bf16 v[44:47], v[168:171], v[144:147], v[44:47]
	v_mfma_f32_16x16x32_bf16 v[44:47], v[172:175], v[160:163], v[44:47]
	v_mfma_f32_16x16x32_bf16 v[40:43], v[176:179], v[144:147], v[40:43]
	v_mfma_f32_16x16x32_bf16 v[40:43], v[180:183], v[160:163], v[40:43]
	v_mfma_f32_16x16x32_bf16 v[36:39], v[184:187], v[140:143], v[36:39]
	v_mfma_f32_16x16x32_bf16 v[36:39], v[188:191], v[156:159], v[36:39]
	v_mfma_f32_16x16x32_bf16 v[32:35], v[192:195], v[140:143], v[32:35]
	v_mfma_f32_16x16x32_bf16 v[32:35], v[196:199], v[156:159], v[32:35]
	v_mfma_f32_16x16x32_bf16 v[28:31], v[168:171], v[140:143], v[28:31]
	v_mfma_f32_16x16x32_bf16 v[28:31], v[172:175], v[156:159], v[28:31]
	v_mfma_f32_16x16x32_bf16 v[24:27], v[176:179], v[140:143], v[24:27]
	v_mfma_f32_16x16x32_bf16 v[24:27], v[180:183], v[156:159], v[24:27]
	v_mfma_f32_16x16x32_bf16 v[20:23], v[184:187], v[136:139], v[20:23]
	v_mfma_f32_16x16x32_bf16 v[20:23], v[188:191], v[152:155], v[20:23]
	v_mfma_f32_16x16x32_bf16 v[16:19], v[192:195], v[136:139], v[16:19]
	v_mfma_f32_16x16x32_bf16 v[16:19], v[196:199], v[152:155], v[16:19]
	v_mfma_f32_16x16x32_bf16 v[12:15], v[168:171], v[136:139], v[12:15]
	v_mfma_f32_16x16x32_bf16 v[12:15], v[172:175], v[152:155], v[12:15]
	v_mfma_f32_16x16x32_bf16 v[8:11], v[176:179], v[136:139], v[8:11]
	v_mfma_f32_16x16x32_bf16 v[8:11], v[180:183], v[152:155], v[8:11]
	s_branch .LBB0_259

.LBB0_369:
	v_add_u32_e32 v168, 0x10000, v232
	v_add_u32_e32 v180, 0x14000, v232
	v_lshl_add_u64 v[224:225], v[222:223], 0, s[60:61]
	s_add_i32 m0, s9, 0xc000
	s_waitcnt lgkmcnt(0)
	ds_read_b128 v[148:151], v207
	ds_read_b128 v[164:167], v207 offset:1024
	ds_read_b128 v[144:147], v207 offset:2048
	ds_read_b128 v[160:163], v207 offset:3072
	ds_read_b128 v[140:143], v207 offset:4096
	ds_read_b128 v[156:159], v207 offset:5120
	ds_read_b128 v[136:139], v207 offset:6144
	ds_read_b128 v[152:155], v207 offset:7168
	ds_read_b128 v[184:187], v168
	ds_read_b128 v[188:191], v168 offset:1024
	ds_read_b128 v[192:195], v168 offset:2048
	ds_read_b128 v[196:199], v168 offset:3072
	ds_read_b128 v[168:171], v180
	ds_read_b128 v[172:175], v180 offset:1024
	ds_read_b128 v[176:179], v180 offset:2048
	ds_read_b128 v[180:183], v180 offset:3072
	global_load_lds_dwordx4 v[224:225], off
	v_lshl_add_u64 v[224:225], v[220:221], 0, s[60:61]
	s_add_i32 m0, s9, 0xe000
	s_nop 0
	global_load_lds_dwordx4 v[224:225], off
	s_waitcnt vmcnt(8)
	s_waitcnt lgkmcnt(0)
	s_barrier
	s_waitcnt lgkmcnt(0)
	v_mfma_f32_16x16x32_bf16 v[132:135], v[184:187], v[148:151], v[132:135]
	v_mfma_f32_16x16x32_bf16 v[132:135], v[188:191], v[164:167], v[132:135]
	v_mfma_f32_16x16x32_bf16 v[128:131], v[192:195], v[148:151], v[128:131]
	v_mfma_f32_16x16x32_bf16 v[128:131], v[196:199], v[164:167], v[128:131]
	v_mfma_f32_16x16x32_bf16 v[116:119], v[168:171], v[148:151], v[116:119]
	v_mfma_f32_16x16x32_bf16 v[116:119], v[172:175], v[164:167], v[116:119]
	v_mfma_f32_16x16x32_bf16 v[112:115], v[176:179], v[148:151], v[112:115]
	v_mfma_f32_16x16x32_bf16 v[112:115], v[180:183], v[164:167], v[112:115]
	v_mfma_f32_16x16x32_bf16 v[124:127], v[184:187], v[144:147], v[124:127]
	v_mfma_f32_16x16x32_bf16 v[124:127], v[188:191], v[160:163], v[124:127]
	v_mfma_f32_16x16x32_bf16 v[120:123], v[192:195], v[144:147], v[120:123]
	v_mfma_f32_16x16x32_bf16 v[120:123], v[196:199], v[160:163], v[120:123]
	v_mfma_f32_16x16x32_bf16 v[100:103], v[168:171], v[144:147], v[100:103]
	v_mfma_f32_16x16x32_bf16 v[100:103], v[172:175], v[160:163], v[100:103]
	v_mfma_f32_16x16x32_bf16 v[96:99], v[176:179], v[144:147], v[96:99]
	v_mfma_f32_16x16x32_bf16 v[96:99], v[180:183], v[160:163], v[96:99]
	v_mfma_f32_16x16x32_bf16 v[108:111], v[184:187], v[140:143], v[108:111]
	v_mfma_f32_16x16x32_bf16 v[108:111], v[188:191], v[156:159], v[108:111]
	v_mfma_f32_16x16x32_bf16 v[104:107], v[192:195], v[140:143], v[104:107]
	v_mfma_f32_16x16x32_bf16 v[104:107], v[196:199], v[156:159], v[104:107]
	v_mfma_f32_16x16x32_bf16 v[84:87], v[168:171], v[140:143], v[84:87]
	v_mfma_f32_16x16x32_bf16 v[84:87], v[172:175], v[156:159], v[84:87]
	v_mfma_f32_16x16x32_bf16 v[80:83], v[176:179], v[140:143], v[80:83]
	v_mfma_f32_16x16x32_bf16 v[80:83], v[180:183], v[156:159], v[80:83]
	v_mfma_f32_16x16x32_bf16 v[92:95], v[184:187], v[136:139], v[92:95]
	v_mfma_f32_16x16x32_bf16 v[92:95], v[188:191], v[152:155], v[92:95]
	v_mfma_f32_16x16x32_bf16 v[88:91], v[192:195], v[136:139], v[88:91]
	v_mfma_f32_16x16x32_bf16 v[88:91], v[196:199], v[152:155], v[88:91]
	v_mfma_f32_16x16x32_bf16 v[76:79], v[168:171], v[136:139], v[76:79]
	v_mfma_f32_16x16x32_bf16 v[76:79], v[172:175], v[152:155], v[76:79]
	v_mfma_f32_16x16x32_bf16 v[72:75], v[176:179], v[136:139], v[72:75]
	v_mfma_f32_16x16x32_bf16 v[72:75], v[180:183], v[152:155], v[72:75]
	s_barrier
	v_cndmask_b32_e64 v204, 0, 1, s[58:59]
	v_cmp_ne_u32_e64 s[50:51], 1, v204
	s_andn2_b64 vcc, exec, s[58:59]
	s_cbranch_vccnz .LBB0_371
	ds_read_b128 v[148:151], v207 offset:16384
	ds_read_b128 v[164:167], v207 offset:17408
	ds_read_b128 v[144:147], v207 offset:18432
	ds_read_b128 v[160:163], v207 offset:19456
	ds_read_b128 v[140:143], v207 offset:20480
	ds_read_b128 v[156:159], v207 offset:21504
	ds_read_b128 v[136:139], v207 offset:22528
	ds_read_b128 v[152:155], v207 offset:23552
.LBB0_371:
	s_add_u32 s12, s24, s60
	s_addc_u32 s13, s25, s61
	s_add_u32 s14, s12, 0x100
	s_addc_u32 s15, s13, 0
	s_add_u32 s73, s26, s60
	s_addc_u32 s74, s27, s61
	s_cmpk_eq_i32 s60, 0xf00
	s_cselect_b64 s[52:53], -1, 0
	s_and_b64 s[12:13], s[52:53], exec
	s_cselect_b32 s13, s37, s74
	s_cselect_b32 s12, s43, s73
	s_mov_b32 m0, s38
	s_cselect_b32 s15, s7, s15
	s_cselect_b32 s14, s33, s14
	v_lshl_add_u64 v[224:225], s[12:13], 0, v[208:209]
	s_add_u32 s74, s12, 0x80000
	global_load_lds_dwordx4 v[224:225], off
	v_lshl_add_u64 v[226:227], s[12:13], 0, v[212:213]
	s_mov_b32 m0, s39
	s_addc_u32 s75, s13, 0
	global_load_lds_dwordx4 v[226:227], off
	v_lshl_add_u64 v[228:229], s[74:75], 0, v[208:209]
	s_mov_b32 m0, s40
	v_lshl_add_u64 v[230:231], s[14:15], 0, v[210:211]
	global_load_lds_dwordx4 v[228:229], off
	v_lshl_add_u64 v[228:229], s[74:75], 0, v[212:213]
	s_mov_b32 m0, s41
	s_and_b64 vcc, exec, s[50:51]
	global_load_lds_dwordx4 v[228:229], off
	v_lshl_add_u64 v[228:229], s[14:15], 0, v[4:5]
	s_mov_b32 m0, s9
	s_nop 0
	global_load_lds_dwordx4 v[228:229], off
	s_mov_b32 m0, s47
	s_nop 0
	global_load_lds_dwordx4 v[230:231], off
	s_waitcnt vmcnt(8)
	s_waitcnt lgkmcnt(0)
	s_barrier
	s_cbranch_vccnz .LBB0_373
	s_waitcnt lgkmcnt(0)
	v_mfma_f32_16x16x32_bf16 v[68:71], v[184:187], v[148:151], v[68:71]
	v_mfma_f32_16x16x32_bf16 v[68:71], v[188:191], v[164:167], v[68:71]
	v_mfma_f32_16x16x32_bf16 v[64:67], v[192:195], v[148:151], v[64:67]
	v_mfma_f32_16x16x32_bf16 v[64:67], v[196:199], v[164:167], v[64:67]
	v_mfma_f32_16x16x32_bf16 v[60:63], v[168:171], v[148:151], v[60:63]
	v_mfma_f32_16x16x32_bf16 v[60:63], v[172:175], v[164:167], v[60:63]
	v_mfma_f32_16x16x32_bf16 v[56:59], v[176:179], v[148:151], v[56:59]
	v_mfma_f32_16x16x32_bf16 v[56:59], v[180:183], v[164:167], v[56:59]
	v_mfma_f32_16x16x32_bf16 v[52:55], v[184:187], v[144:147], v[52:55]
	v_mfma_f32_16x16x32_bf16 v[52:55], v[188:191], v[160:163], v[52:55]
	v_mfma_f32_16x16x32_bf16 v[48:51], v[192:195], v[144:147], v[48:51]
	v_mfma_f32_16x16x32_bf16 v[48:51], v[196:199], v[160:163], v[48:51]
	v_mfma_f32_16x16x32_bf16 v[44:47], v[168:171], v[144:147], v[44:47]
	v_mfma_f32_16x16x32_bf16 v[44:47], v[172:175], v[160:163], v[44:47]
	v_mfma_f32_16x16x32_bf16 v[40:43], v[176:179], v[144:147], v[40:43]
	v_mfma_f32_16x16x32_bf16 v[40:43], v[180:183], v[160:163], v[40:43]
	v_mfma_f32_16x16x32_bf16 v[36:39], v[184:187], v[140:143], v[36:39]
	v_mfma_f32_16x16x32_bf16 v[36:39], v[188:191], v[156:159], v[36:39]
	v_mfma_f32_16x16x32_bf16 v[32:35], v[192:195], v[140:143], v[32:35]
	v_mfma_f32_16x16x32_bf16 v[32:35], v[196:199], v[156:159], v[32:35]
	v_mfma_f32_16x16x32_bf16 v[28:31], v[168:171], v[140:143], v[28:31]
	v_mfma_f32_16x16x32_bf16 v[28:31], v[172:175], v[156:159], v[28:31]
	v_mfma_f32_16x16x32_bf16 v[24:27], v[176:179], v[140:143], v[24:27]
	v_mfma_f32_16x16x32_bf16 v[24:27], v[180:183], v[156:159], v[24:27]
	v_mfma_f32_16x16x32_bf16 v[20:23], v[184:187], v[136:139], v[20:23]
	v_mfma_f32_16x16x32_bf16 v[20:23], v[188:191], v[152:155], v[20:23]
	v_mfma_f32_16x16x32_bf16 v[16:19], v[192:195], v[136:139], v[16:19]
	v_mfma_f32_16x16x32_bf16 v[16:19], v[196:199], v[152:155], v[16:19]
	v_mfma_f32_16x16x32_bf16 v[12:15], v[168:171], v[136:139], v[12:15]
	v_mfma_f32_16x16x32_bf16 v[12:15], v[172:175], v[152:155], v[12:15]
	v_mfma_f32_16x16x32_bf16 v[8:11], v[176:179], v[136:139], v[8:11]
	v_mfma_f32_16x16x32_bf16 v[8:11], v[180:183], v[152:155], v[8:11]
.LBB0_373:
	s_barrier
	v_cndmask_b32_e64 v241, v219, 0, s[52:53]
	v_cndmask_b32_e64 v240, v218, v2, s[52:53]
	v_lshl_add_u64 v[240:241], s[14:15], 0, v[240:241]
	s_mov_b32 m0, s62
	v_add_u32_e32 v168, 0x18000, v232
	v_add_u32_e32 v180, 0x1c000, v232
	v_lshl_add_u64 v[242:243], v[240:241], 0, v[4:5]
	s_waitcnt lgkmcnt(0)
	ds_read_b128 v[148:151], v207 offset:32768
	ds_read_b128 v[164:167], v207 offset:33792
	ds_read_b128 v[144:147], v207 offset:34816
	ds_read_b128 v[160:163], v207 offset:35840
	ds_read_b128 v[140:143], v207 offset:36864
	ds_read_b128 v[156:159], v207 offset:37888
	ds_read_b128 v[136:139], v207 offset:38912
	ds_read_b128 v[152:155], v207 offset:39936
	ds_read_b128 v[184:187], v168
	ds_read_b128 v[188:191], v168 offset:1024
	ds_read_b128 v[192:195], v168 offset:2048
	ds_read_b128 v[196:199], v168 offset:3072
	ds_read_b128 v[168:171], v180
	ds_read_b128 v[172:175], v180 offset:1024
	ds_read_b128 v[176:179], v180 offset:2048
	ds_read_b128 v[180:183], v180 offset:3072
	global_load_lds_dwordx4 v[242:243], off
	v_lshl_add_u64 v[240:241], v[240:241], 0, v[210:211]
	s_mov_b32 m0, s63
	s_nop 0
	global_load_lds_dwordx4 v[240:241], off
	s_waitcnt vmcnt(8)
	s_waitcnt lgkmcnt(0)
	s_barrier
	s_waitcnt lgkmcnt(0)
	v_mfma_f32_16x16x32_bf16 v[132:135], v[184:187], v[148:151], v[132:135]
	v_mfma_f32_16x16x32_bf16 v[132:135], v[188:191], v[164:167], v[132:135]
	v_mfma_f32_16x16x32_bf16 v[128:131], v[192:195], v[148:151], v[128:131]
	v_mfma_f32_16x16x32_bf16 v[128:131], v[196:199], v[164:167], v[128:131]
	v_mfma_f32_16x16x32_bf16 v[116:119], v[168:171], v[148:151], v[116:119]
	v_mfma_f32_16x16x32_bf16 v[116:119], v[172:175], v[164:167], v[116:119]
	v_mfma_f32_16x16x32_bf16 v[112:115], v[176:179], v[148:151], v[112:115]
	v_mfma_f32_16x16x32_bf16 v[112:115], v[180:183], v[164:167], v[112:115]
	v_mfma_f32_16x16x32_bf16 v[124:127], v[184:187], v[144:147], v[124:127]
	v_mfma_f32_16x16x32_bf16 v[124:127], v[188:191], v[160:163], v[124:127]
	v_mfma_f32_16x16x32_bf16 v[120:123], v[192:195], v[144:147], v[120:123]
	v_mfma_f32_16x16x32_bf16 v[120:123], v[196:199], v[160:163], v[120:123]
	v_mfma_f32_16x16x32_bf16 v[100:103], v[168:171], v[144:147], v[100:103]
	v_mfma_f32_16x16x32_bf16 v[100:103], v[172:175], v[160:163], v[100:103]
	v_mfma_f32_16x16x32_bf16 v[96:99], v[176:179], v[144:147], v[96:99]
	v_mfma_f32_16x16x32_bf16 v[96:99], v[180:183], v[160:163], v[96:99]
	v_mfma_f32_16x16x32_bf16 v[108:111], v[184:187], v[140:143], v[108:111]
	v_mfma_f32_16x16x32_bf16 v[108:111], v[188:191], v[156:159], v[108:111]
	v_mfma_f32_16x16x32_bf16 v[104:107], v[192:195], v[140:143], v[104:107]
	v_mfma_f32_16x16x32_bf16 v[104:107], v[196:199], v[156:159], v[104:107]
	v_mfma_f32_16x16x32_bf16 v[84:87], v[168:171], v[140:143], v[84:87]
	v_mfma_f32_16x16x32_bf16 v[84:87], v[172:175], v[156:159], v[84:87]
	v_mfma_f32_16x16x32_bf16 v[80:83], v[176:179], v[140:143], v[80:83]
	v_mfma_f32_16x16x32_bf16 v[80:83], v[180:183], v[156:159], v[80:83]
	v_mfma_f32_16x16x32_bf16 v[92:95], v[184:187], v[136:139], v[92:95]
	v_mfma_f32_16x16x32_bf16 v[92:95], v[188:191], v[152:155], v[92:95]
	v_mfma_f32_16x16x32_bf16 v[88:91], v[192:195], v[136:139], v[88:91]
	v_mfma_f32_16x16x32_bf16 v[88:91], v[196:199], v[152:155], v[88:91]
	v_mfma_f32_16x16x32_bf16 v[76:79], v[168:171], v[136:139], v[76:79]
	v_mfma_f32_16x16x32_bf16 v[76:79], v[172:175], v[152:155], v[76:79]
	v_mfma_f32_16x16x32_bf16 v[72:75], v[176:179], v[136:139], v[72:75]
	v_mfma_f32_16x16x32_bf16 v[72:75], v[180:183], v[152:155], v[72:75]
	s_barrier
	s_and_b64 vcc, exec, s[50:51]
	s_cbranch_vccnz .LBB0_375
	ds_read_b128 v[148:151], v207 offset:49152
	ds_read_b128 v[164:167], v207 offset:50176
	ds_read_b128 v[144:147], v207 offset:51200
	ds_read_b128 v[160:163], v207 offset:52224
	ds_read_b128 v[140:143], v207 offset:53248
	ds_read_b128 v[156:159], v207 offset:54272
	ds_read_b128 v[136:139], v207 offset:55296
	ds_read_b128 v[152:155], v207 offset:56320

.LBB0_559:
	v_add_u32_e32 v168, 0x10000, v240
	v_add_u32_e32 v180, 0x14000, v240
	v_lshl_add_u64 v[226:227], v[224:225], 0, s[64:65]
	s_add_i32 m0, s38, 0xc000
	s_waitcnt lgkmcnt(0)
	ds_read_b128 v[148:151], v239
	ds_read_b128 v[164:167], v239 offset:1024
	ds_read_b128 v[144:147], v239 offset:2048
	ds_read_b128 v[160:163], v239 offset:3072
	ds_read_b128 v[140:143], v239 offset:4096
	ds_read_b128 v[156:159], v239 offset:5120
	ds_read_b128 v[136:139], v239 offset:6144
	ds_read_b128 v[152:155], v239 offset:7168
	ds_read_b128 v[184:187], v168
	ds_read_b128 v[188:191], v168 offset:1024
	ds_read_b128 v[192:195], v168 offset:2048
	ds_read_b128 v[196:199], v168 offset:3072
	ds_read_b128 v[168:171], v180
	ds_read_b128 v[172:175], v180 offset:1024
	ds_read_b128 v[176:179], v180 offset:2048
	ds_read_b128 v[180:183], v180 offset:3072
	global_load_lds_dwordx4 v[226:227], off
	v_lshl_add_u64 v[226:227], v[222:223], 0, s[64:65]
	s_add_i32 m0, s38, 0xe000
	s_nop 0
	global_load_lds_dwordx4 v[226:227], off
	s_waitcnt vmcnt(8)
	s_waitcnt lgkmcnt(0)
	s_barrier
	s_waitcnt lgkmcnt(0)
	v_mfma_f32_16x16x32_bf16 v[132:135], v[184:187], v[148:151], v[132:135]
	v_mfma_f32_16x16x32_bf16 v[132:135], v[188:191], v[164:167], v[132:135]
	v_mfma_f32_16x16x32_bf16 v[128:131], v[192:195], v[148:151], v[128:131]
	v_mfma_f32_16x16x32_bf16 v[128:131], v[196:199], v[164:167], v[128:131]
	v_mfma_f32_16x16x32_bf16 v[124:127], v[168:171], v[148:151], v[124:127]
	v_mfma_f32_16x16x32_bf16 v[124:127], v[172:175], v[164:167], v[124:127]
	v_mfma_f32_16x16x32_bf16 v[120:123], v[176:179], v[148:151], v[120:123]
	v_mfma_f32_16x16x32_bf16 v[120:123], v[180:183], v[164:167], v[120:123]
	v_mfma_f32_16x16x32_bf16 v[116:119], v[184:187], v[144:147], v[116:119]
	v_mfma_f32_16x16x32_bf16 v[116:119], v[188:191], v[160:163], v[116:119]
	v_mfma_f32_16x16x32_bf16 v[112:115], v[192:195], v[144:147], v[112:115]
	v_mfma_f32_16x16x32_bf16 v[112:115], v[196:199], v[160:163], v[112:115]
	v_mfma_f32_16x16x32_bf16 v[108:111], v[168:171], v[144:147], v[108:111]
	v_mfma_f32_16x16x32_bf16 v[108:111], v[172:175], v[160:163], v[108:111]
	v_mfma_f32_16x16x32_bf16 v[104:107], v[176:179], v[144:147], v[104:107]
	v_mfma_f32_16x16x32_bf16 v[104:107], v[180:183], v[160:163], v[104:107]
	v_mfma_f32_16x16x32_bf16 v[100:103], v[184:187], v[140:143], v[100:103]
	v_mfma_f32_16x16x32_bf16 v[100:103], v[188:191], v[156:159], v[100:103]
	v_mfma_f32_16x16x32_bf16 v[96:99], v[192:195], v[140:143], v[96:99]
	v_mfma_f32_16x16x32_bf16 v[96:99], v[196:199], v[156:159], v[96:99]
	v_mfma_f32_16x16x32_bf16 v[92:95], v[168:171], v[140:143], v[92:95]
	v_mfma_f32_16x16x32_bf16 v[92:95], v[172:175], v[156:159], v[92:95]
	v_mfma_f32_16x16x32_bf16 v[88:91], v[176:179], v[140:143], v[88:91]
	v_mfma_f32_16x16x32_bf16 v[88:91], v[180:183], v[156:159], v[88:91]
	v_mfma_f32_16x16x32_bf16 v[84:87], v[184:187], v[136:139], v[84:87]
	v_mfma_f32_16x16x32_bf16 v[84:87], v[188:191], v[152:155], v[84:87]
	v_mfma_f32_16x16x32_bf16 v[80:83], v[192:195], v[136:139], v[80:83]
	v_mfma_f32_16x16x32_bf16 v[80:83], v[196:199], v[152:155], v[80:83]
	v_mfma_f32_16x16x32_bf16 v[76:79], v[168:171], v[136:139], v[76:79]
	v_mfma_f32_16x16x32_bf16 v[76:79], v[172:175], v[152:155], v[76:79]
	v_mfma_f32_16x16x32_bf16 v[72:75], v[176:179], v[136:139], v[72:75]
	v_mfma_f32_16x16x32_bf16 v[72:75], v[180:183], v[152:155], v[72:75]
	s_barrier
	v_cndmask_b32_e64 v204, 0, 1, s[62:63]
	v_cmp_ne_u32_e64 s[50:51], 1, v204
	s_andn2_b64 vcc, exec, s[62:63]
	s_cbranch_vccnz .LBB0_561
	ds_read_b128 v[148:151], v239 offset:16384
	ds_read_b128 v[164:167], v239 offset:17408
	ds_read_b128 v[144:147], v239 offset:18432
	ds_read_b128 v[160:163], v239 offset:19456
	ds_read_b128 v[140:143], v239 offset:20480
	ds_read_b128 v[156:159], v239 offset:21504
	ds_read_b128 v[136:139], v239 offset:22528
	ds_read_b128 v[152:155], v239 offset:23552
.LBB0_561:
	s_add_u32 s12, s60, s64
	s_addc_u32 s13, s61, s65
	s_add_u32 s14, s12, 0x100
	s_addc_u32 s15, s13, 0
	s_add_u32 s79, s26, s64
	s_addc_u32 s80, s27, s65
	s_cmpk_eq_i32 s64, 0x300
	s_cselect_b64 s[52:53], -1, 0
	s_and_b64 s[12:13], s[52:53], exec
	s_cselect_b32 s13, s17, s80
	s_cselect_b32 s12, s35, s79
	s_mov_b32 m0, s39
	s_cselect_b32 s15, s21, s15
	s_cselect_b32 s14, s33, s14
	v_lshl_add_u64 v[226:227], s[12:13], 0, v[4:5]
	s_add_u32 s80, s12, 0x20000
	global_load_lds_dwordx4 v[226:227], off
	v_lshl_add_u64 v[228:229], s[12:13], 0, v[208:209]
	s_mov_b32 m0, s40
	s_addc_u32 s81, s13, 0
	global_load_lds_dwordx4 v[228:229], off
	v_lshl_add_u64 v[230:231], s[80:81], 0, v[4:5]
	s_mov_b32 m0, s41
	v_lshl_add_u64 v[232:233], s[14:15], 0, v[208:209]
	global_load_lds_dwordx4 v[230:231], off
	v_lshl_add_u64 v[230:231], s[80:81], 0, v[208:209]
	s_mov_b32 m0, s47
	s_and_b64 vcc, exec, s[50:51]
	global_load_lds_dwordx4 v[230:231], off
	v_lshl_add_u64 v[230:231], s[14:15], 0, v[4:5]
	s_mov_b32 m0, s38
	s_nop 0
	global_load_lds_dwordx4 v[230:231], off
	s_mov_b32 m0, s59
	s_nop 0
	global_load_lds_dwordx4 v[232:233], off
	s_waitcnt vmcnt(8)
	s_waitcnt lgkmcnt(0)
	s_barrier
	s_cbranch_vccnz .LBB0_563
	s_waitcnt lgkmcnt(0)
	v_mfma_f32_16x16x32_bf16 v[68:71], v[184:187], v[148:151], v[68:71]
	v_mfma_f32_16x16x32_bf16 v[68:71], v[188:191], v[164:167], v[68:71]
	v_mfma_f32_16x16x32_bf16 v[64:67], v[192:195], v[148:151], v[64:67]
	v_mfma_f32_16x16x32_bf16 v[64:67], v[196:199], v[164:167], v[64:67]
	v_mfma_f32_16x16x32_bf16 v[60:63], v[168:171], v[148:151], v[60:63]
	v_mfma_f32_16x16x32_bf16 v[60:63], v[172:175], v[164:167], v[60:63]
	v_mfma_f32_16x16x32_bf16 v[56:59], v[176:179], v[148:151], v[56:59]
	v_mfma_f32_16x16x32_bf16 v[56:59], v[180:183], v[164:167], v[56:59]
	v_mfma_f32_16x16x32_bf16 v[52:55], v[184:187], v[144:147], v[52:55]
	v_mfma_f32_16x16x32_bf16 v[52:55], v[188:191], v[160:163], v[52:55]
	v_mfma_f32_16x16x32_bf16 v[48:51], v[192:195], v[144:147], v[48:51]
	v_mfma_f32_16x16x32_bf16 v[48:51], v[196:199], v[160:163], v[48:51]
	v_mfma_f32_16x16x32_bf16 v[44:47], v[168:171], v[144:147], v[44:47]
	v_mfma_f32_16x16x32_bf16 v[44:47], v[172:175], v[160:163], v[44:47]
	v_mfma_f32_16x16x32_bf16 v[40:43], v[176:179], v[144:147], v[40:43]
	v_mfma_f32_16x16x32_bf16 v[40:43], v[180:183], v[160:163], v[40:43]
	v_mfma_f32_16x16x32_bf16 v[36:39], v[184:187], v[140:143], v[36:39]
	v_mfma_f32_16x16x32_bf16 v[36:39], v[188:191], v[156:159], v[36:39]
	v_mfma_f32_16x16x32_bf16 v[32:35], v[192:195], v[140:143], v[32:35]
	v_mfma_f32_16x16x32_bf16 v[32:35], v[196:199], v[156:159], v[32:35]
	v_mfma_f32_16x16x32_bf16 v[28:31], v[168:171], v[140:143], v[28:31]
	v_mfma_f32_16x16x32_bf16 v[28:31], v[172:175], v[156:159], v[28:31]
	v_mfma_f32_16x16x32_bf16 v[24:27], v[176:179], v[140:143], v[24:27]
	v_mfma_f32_16x16x32_bf16 v[24:27], v[180:183], v[156:159], v[24:27]
	v_mfma_f32_16x16x32_bf16 v[20:23], v[184:187], v[136:139], v[20:23]
	v_mfma_f32_16x16x32_bf16 v[20:23], v[188:191], v[152:155], v[20:23]
	v_mfma_f32_16x16x32_bf16 v[16:19], v[192:195], v[136:139], v[16:19]
	v_mfma_f32_16x16x32_bf16 v[16:19], v[196:199], v[152:155], v[16:19]
	v_mfma_f32_16x16x32_bf16 v[12:15], v[168:171], v[136:139], v[12:15]
	v_mfma_f32_16x16x32_bf16 v[12:15], v[172:175], v[152:155], v[12:15]
	v_mfma_f32_16x16x32_bf16 v[8:11], v[176:179], v[136:139], v[8:11]
	v_mfma_f32_16x16x32_bf16 v[8:11], v[180:183], v[152:155], v[8:11]
.LBB0_563:
	s_barrier
	v_cndmask_b32_e64 v243, v221, 0, s[52:53]
	v_cndmask_b32_e64 v242, v220, v2, s[52:53]
	v_lshl_add_u64 v[242:243], s[14:15], 0, v[242:243]
	s_mov_b32 m0, s66
	v_add_u32_e32 v168, 0x18000, v240
	v_add_u32_e32 v180, 0x1c000, v240
	v_lshl_add_u64 v[204:205], v[242:243], 0, v[4:5]
	s_waitcnt lgkmcnt(0)
	ds_read_b128 v[148:151], v239 offset:32768
	ds_read_b128 v[164:167], v239 offset:33792
	ds_read_b128 v[144:147], v239 offset:34816
	ds_read_b128 v[160:163], v239 offset:35840
	ds_read_b128 v[140:143], v239 offset:36864
	ds_read_b128 v[156:159], v239 offset:37888
	ds_read_b128 v[136:139], v239 offset:38912
	ds_read_b128 v[152:155], v239 offset:39936
	ds_read_b128 v[184:187], v168
	ds_read_b128 v[188:191], v168 offset:1024
	ds_read_b128 v[192:195], v168 offset:2048
	ds_read_b128 v[196:199], v168 offset:3072
	ds_read_b128 v[168:171], v180
	ds_read_b128 v[172:175], v180 offset:1024
	ds_read_b128 v[176:179], v180 offset:2048
	ds_read_b128 v[180:183], v180 offset:3072
	global_load_lds_dwordx4 v[204:205], off
	v_lshl_add_u64 v[204:205], v[242:243], 0, v[208:209]
	s_mov_b32 m0, s67
	s_nop 0
	global_load_lds_dwordx4 v[204:205], off
	s_waitcnt vmcnt(8)
	s_waitcnt lgkmcnt(0)
	s_barrier
	s_waitcnt lgkmcnt(0)
	v_mfma_f32_16x16x32_bf16 v[132:135], v[184:187], v[148:151], v[132:135]
	v_mfma_f32_16x16x32_bf16 v[132:135], v[188:191], v[164:167], v[132:135]
	v_mfma_f32_16x16x32_bf16 v[128:131], v[192:195], v[148:151], v[128:131]
	v_mfma_f32_16x16x32_bf16 v[128:131], v[196:199], v[164:167], v[128:131]
	v_mfma_f32_16x16x32_bf16 v[124:127], v[168:171], v[148:151], v[124:127]
	v_mfma_f32_16x16x32_bf16 v[124:127], v[172:175], v[164:167], v[124:127]
	v_mfma_f32_16x16x32_bf16 v[120:123], v[176:179], v[148:151], v[120:123]
	v_mfma_f32_16x16x32_bf16 v[120:123], v[180:183], v[164:167], v[120:123]
	v_mfma_f32_16x16x32_bf16 v[116:119], v[184:187], v[144:147], v[116:119]
	v_mfma_f32_16x16x32_bf16 v[116:119], v[188:191], v[160:163], v[116:119]
	v_mfma_f32_16x16x32_bf16 v[112:115], v[192:195], v[144:147], v[112:115]
	v_mfma_f32_16x16x32_bf16 v[112:115], v[196:199], v[160:163], v[112:115]
	v_mfma_f32_16x16x32_bf16 v[108:111], v[168:171], v[144:147], v[108:111]
	v_mfma_f32_16x16x32_bf16 v[108:111], v[172:175], v[160:163], v[108:111]
	v_mfma_f32_16x16x32_bf16 v[104:107], v[176:179], v[144:147], v[104:107]
	v_mfma_f32_16x16x32_bf16 v[104:107], v[180:183], v[160:163], v[104:107]
	v_mfma_f32_16x16x32_bf16 v[100:103], v[184:187], v[140:143], v[100:103]
	v_mfma_f32_16x16x32_bf16 v[100:103], v[188:191], v[156:159], v[100:103]
	v_mfma_f32_16x16x32_bf16 v[96:99], v[192:195], v[140:143], v[96:99]
	v_mfma_f32_16x16x32_bf16 v[96:99], v[196:199], v[156:159], v[96:99]
	v_mfma_f32_16x16x32_bf16 v[92:95], v[168:171], v[140:143], v[92:95]
	v_mfma_f32_16x16x32_bf16 v[92:95], v[172:175], v[156:159], v[92:95]
	v_mfma_f32_16x16x32_bf16 v[88:91], v[176:179], v[140:143], v[88:91]
	v_mfma_f32_16x16x32_bf16 v[88:91], v[180:183], v[156:159], v[88:91]
	v_mfma_f32_16x16x32_bf16 v[84:87], v[184:187], v[136:139], v[84:87]
	v_mfma_f32_16x16x32_bf16 v[84:87], v[188:191], v[152:155], v[84:87]
	v_mfma_f32_16x16x32_bf16 v[80:83], v[192:195], v[136:139], v[80:83]
	v_mfma_f32_16x16x32_bf16 v[80:83], v[196:199], v[152:155], v[80:83]
	v_mfma_f32_16x16x32_bf16 v[76:79], v[168:171], v[136:139], v[76:79]
	v_mfma_f32_16x16x32_bf16 v[76:79], v[172:175], v[152:155], v[76:79]
	v_mfma_f32_16x16x32_bf16 v[72:75], v[176:179], v[136:139], v[72:75]
	v_mfma_f32_16x16x32_bf16 v[72:75], v[180:183], v[152:155], v[72:75]
	s_barrier
	s_and_b64 vcc, exec, s[50:51]
	s_cbranch_vccnz .LBB0_565
	ds_read_b128 v[148:151], v239 offset:49152
	ds_read_b128 v[164:167], v239 offset:50176
	ds_read_b128 v[144:147], v239 offset:51200
	ds_read_b128 v[160:163], v239 offset:52224
	ds_read_b128 v[140:143], v239 offset:53248
	ds_read_b128 v[156:159], v239 offset:54272
	ds_read_b128 v[136:139], v239 offset:55296
	ds_read_b128 v[152:155], v239 offset:56320
.LBB0_565:
	s_mov_b32 m0, s70
	v_lshl_add_u64 v[204:205], v[226:227], 0, s[0:1]
	s_add_u32 s12, s12, 0x20080
	global_load_lds_dwordx4 v[204:205], off
	v_lshl_add_u64 v[204:205], v[228:229], 0, s[0:1]
	s_mov_b32 m0, s71
	s_addc_u32 s13, s13, 0
	global_load_lds_dwordx4 v[204:205], off
	v_lshl_add_u64 v[204:205], s[12:13], 0, v[4:5]
	s_mov_b32 m0, s74
	s_and_b64 vcc, exec, s[50:51]
	global_load_lds_dwordx4 v[204:205], off
	v_lshl_add_u64 v[204:205], s[12:13], 0, v[208:209]
	s_mov_b32 m0, s75
	s_nop 0
	global_load_lds_dwordx4 v[204:205], off
	v_lshl_add_u64 v[204:205], v[230:231], 0, s[0:1]
	s_mov_b32 m0, s72
	s_nop 0
	global_load_lds_dwordx4 v[204:205], off
	v_lshl_add_u64 v[204:205], v[232:233], 0, s[0:1]
	s_mov_b32 m0, s73
	s_nop 0
	global_load_lds_dwordx4 v[204:205], off
	s_waitcnt vmcnt(8)
	s_waitcnt lgkmcnt(0)
	s_barrier
	s_cbranch_vccnz .LBB0_558
	s_waitcnt lgkmcnt(0)
	v_mfma_f32_16x16x32_bf16 v[68:71], v[184:187], v[148:151], v[68:71]
	v_mfma_f32_16x16x32_bf16 v[68:71], v[188:191], v[164:167], v[68:71]
	v_mfma_f32_16x16x32_bf16 v[64:67], v[192:195], v[148:151], v[64:67]
	v_mfma_f32_16x16x32_bf16 v[64:67], v[196:199], v[164:167], v[64:67]
	v_mfma_f32_16x16x32_bf16 v[60:63], v[168:171], v[148:151], v[60:63]
	v_mfma_f32_16x16x32_bf16 v[60:63], v[172:175], v[164:167], v[60:63]
	v_mfma_f32_16x16x32_bf16 v[56:59], v[176:179], v[148:151], v[56:59]
	v_mfma_f32_16x16x32_bf16 v[56:59], v[180:183], v[164:167], v[56:59]
	v_mfma_f32_16x16x32_bf16 v[52:55], v[184:187], v[144:147], v[52:55]
	v_mfma_f32_16x16x32_bf16 v[52:55], v[188:191], v[160:163], v[52:55]
	v_mfma_f32_16x16x32_bf16 v[48:51], v[192:195], v[144:147], v[48:51]
	v_mfma_f32_16x16x32_bf16 v[48:51], v[196:199], v[160:163], v[48:51]
	v_mfma_f32_16x16x32_bf16 v[44:47], v[168:171], v[144:147], v[44:47]
	v_mfma_f32_16x16x32_bf16 v[44:47], v[172:175], v[160:163], v[44:47]
	v_mfma_f32_16x16x32_bf16 v[40:43], v[176:179], v[144:147], v[40:43]
	v_mfma_f32_16x16x32_bf16 v[40:43], v[180:183], v[160:163], v[40:43]
	v_mfma_f32_16x16x32_bf16 v[36:39], v[184:187], v[140:143], v[36:39]
	v_mfma_f32_16x16x32_bf16 v[36:39], v[188:191], v[156:159], v[36:39]
	v_mfma_f32_16x16x32_bf16 v[32:35], v[192:195], v[140:143], v[32:35]
	v_mfma_f32_16x16x32_bf16 v[32:35], v[196:199], v[156:159], v[32:35]
	v_mfma_f32_16x16x32_bf16 v[28:31], v[168:171], v[140:143], v[28:31]
	v_mfma_f32_16x16x32_bf16 v[28:31], v[172:175], v[156:159], v[28:31]
	v_mfma_f32_16x16x32_bf16 v[24:27], v[176:179], v[140:143], v[24:27]
	v_mfma_f32_16x16x32_bf16 v[24:27], v[180:183], v[156:159], v[24:27]
	v_mfma_f32_16x16x32_bf16 v[20:23], v[184:187], v[136:139], v[20:23]
	v_mfma_f32_16x16x32_bf16 v[20:23], v[188:191], v[152:155], v[20:23]
	v_mfma_f32_16x16x32_bf16 v[16:19], v[192:195], v[136:139], v[16:19]
	v_mfma_f32_16x16x32_bf16 v[16:19], v[196:199], v[152:155], v[16:19]
	v_mfma_f32_16x16x32_bf16 v[12:15], v[168:171], v[136:139], v[12:15]
	v_mfma_f32_16x16x32_bf16 v[12:15], v[172:175], v[152:155], v[12:15]
	v_mfma_f32_16x16x32_bf16 v[8:11], v[176:179], v[136:139], v[8:11]
	v_mfma_f32_16x16x32_bf16 v[8:11], v[180:183], v[152:155], v[8:11]
	s_branch .LBB0_558

.LBB0_620:
	s_add_u32 s12, s42, 0xfffe0080
	s_addc_u32 s13, s43, -1
	s_cmp_eq_u32 s57, 4
	s_cselect_b32 s15, s17, s13
	s_cselect_b32 s14, s33, s12
	s_cselect_b32 s13, s11, s27
	s_cselect_b32 s12, s37, s26
	s_add_i32 s58, 0, 0x10000
	v_add_u32_e32 v136, s58, v1
	s_add_i32 s60, 0, 0x14000
	ds_read_b128 v[150:153], v7
	ds_read_b128 v[154:157], v7 offset:1024
	ds_read_b128 v[158:161], v7 offset:2048
	ds_read_b128 v[162:165], v7 offset:3072
	ds_read_b128 v[166:169], v7 offset:4096
	ds_read_b128 v[170:173], v7 offset:5120
	ds_read_b128 v[174:177], v7 offset:6144
	ds_read_b128 v[178:181], v7 offset:7168
	ds_read_b128 v[182:185], v136
	ds_read_b128 v[186:189], v136 offset:1024
	ds_read_b128 v[190:193], v136 offset:2048
	ds_read_b128 v[194:197], v136 offset:3072
	v_add_u32_e32 v136, s60, v1
	ds_read_b128 v[208:211], v136
	ds_read_b128 v[212:215], v136 offset:1024
	ds_read_b128 v[216:219], v136 offset:2048
	ds_read_b128 v[220:223], v136 offset:3072
	v_lshl_add_u64 v[136:137], s[42:43], 0, v[146:147]
	s_add_i32 m0, s38, 0xc000
	s_nop 0
	global_load_lds_dwordx4 v[136:137], off
	v_lshl_add_u64 v[136:137], s[42:43], 0, v[148:149]
	s_add_i32 m0, s38, 0xe000
	s_nop 0
	global_load_lds_dwordx4 v[136:137], off
	s_waitcnt vmcnt(8)
	s_waitcnt lgkmcnt(0)
	s_barrier
	s_waitcnt lgkmcnt(0)
	v_mfma_f32_16x16x32_bf16 v[132:135], v[182:185], v[150:153], v[132:135]
	v_mfma_f32_16x16x32_bf16 v[132:135], v[186:189], v[154:157], v[132:135]
	v_mfma_f32_16x16x32_bf16 v[128:131], v[190:193], v[150:153], v[128:131]
	v_mfma_f32_16x16x32_bf16 v[128:131], v[194:197], v[154:157], v[128:131]
	v_mfma_f32_16x16x32_bf16 v[112:115], v[208:211], v[150:153], v[112:115]
	v_mfma_f32_16x16x32_bf16 v[112:115], v[212:215], v[154:157], v[112:115]
	v_mfma_f32_16x16x32_bf16 v[104:107], v[216:219], v[150:153], v[104:107]
	v_mfma_f32_16x16x32_bf16 v[104:107], v[220:223], v[154:157], v[104:107]
	v_mfma_f32_16x16x32_bf16 v[124:127], v[182:185], v[158:161], v[124:127]
	v_mfma_f32_16x16x32_bf16 v[124:127], v[186:189], v[162:165], v[124:127]
	v_mfma_f32_16x16x32_bf16 v[120:123], v[190:193], v[158:161], v[120:123]
	v_mfma_f32_16x16x32_bf16 v[120:123], v[194:197], v[162:165], v[120:123]
	v_mfma_f32_16x16x32_bf16 v[96:99], v[208:211], v[158:161], v[96:99]
	v_mfma_f32_16x16x32_bf16 v[96:99], v[212:215], v[162:165], v[96:99]
	v_mfma_f32_16x16x32_bf16 v[88:91], v[216:219], v[158:161], v[88:91]
	v_mfma_f32_16x16x32_bf16 v[88:91], v[220:223], v[162:165], v[88:91]
	v_mfma_f32_16x16x32_bf16 v[116:119], v[182:185], v[166:169], v[116:119]
	v_mfma_f32_16x16x32_bf16 v[116:119], v[186:189], v[170:173], v[116:119]
	v_mfma_f32_16x16x32_bf16 v[108:111], v[190:193], v[166:169], v[108:111]
	v_mfma_f32_16x16x32_bf16 v[108:111], v[194:197], v[170:173], v[108:111]
	v_mfma_f32_16x16x32_bf16 v[84:87], v[208:211], v[166:169], v[84:87]
	v_mfma_f32_16x16x32_bf16 v[84:87], v[212:215], v[170:173], v[84:87]
	v_mfma_f32_16x16x32_bf16 v[80:83], v[216:219], v[166:169], v[80:83]
	v_mfma_f32_16x16x32_bf16 v[80:83], v[220:223], v[170:173], v[80:83]
	v_mfma_f32_16x16x32_bf16 v[100:103], v[182:185], v[174:177], v[100:103]
	v_mfma_f32_16x16x32_bf16 v[100:103], v[186:189], v[178:181], v[100:103]
	v_mfma_f32_16x16x32_bf16 v[92:95], v[190:193], v[174:177], v[92:95]
	v_mfma_f32_16x16x32_bf16 v[92:95], v[194:197], v[178:181], v[92:95]
	v_mfma_f32_16x16x32_bf16 v[76:79], v[208:211], v[174:177], v[76:79]
	v_mfma_f32_16x16x32_bf16 v[76:79], v[212:215], v[178:181], v[76:79]
	v_mfma_f32_16x16x32_bf16 v[72:75], v[216:219], v[174:177], v[72:75]
	v_mfma_f32_16x16x32_bf16 v[72:75], v[220:223], v[178:181], v[72:75]
	s_barrier
	s_add_i32 s58, s58, s35
	v_lshl_add_u64 v[136:137], s[12:13], 0, v[2:3]
	s_mov_b32 m0, s58
	ds_read_b128 v[150:153], v7 offset:16384
	ds_read_b128 v[154:157], v7 offset:17408
	ds_read_b128 v[158:161], v7 offset:18432
	ds_read_b128 v[162:165], v7 offset:19456
	ds_read_b128 v[166:169], v7 offset:20480
	ds_read_b128 v[170:173], v7 offset:21504
	ds_read_b128 v[174:177], v7 offset:22528
	ds_read_b128 v[178:181], v7 offset:23552
	global_load_lds_dwordx4 v[136:137], off
	s_add_i32 m0, s58, 0x2000
	s_add_u32 s58, s12, 0x20000
	v_lshl_add_u64 v[198:199], s[12:13], 0, v[4:5]
	s_addc_u32 s59, s13, 0
	s_add_i32 s60, s60, s35
	global_load_lds_dwordx4 v[198:199], off
	v_lshl_add_u64 v[204:205], s[58:59], 0, v[2:3]
	s_mov_b32 m0, s60
	v_lshl_add_u64 v[224:225], s[14:15], 0, v[138:139]
	global_load_lds_dwordx4 v[204:205], off
	v_lshl_add_u64 v[204:205], s[58:59], 0, v[4:5]
	s_add_i32 m0, s60, 0x2000
	s_nop 0
	global_load_lds_dwordx4 v[204:205], off
	v_lshl_add_u64 v[204:205], s[14:15], 0, v[140:141]
	s_mov_b32 m0, s38
	s_nop 0
	global_load_lds_dwordx4 v[204:205], off
	s_mov_b32 m0, s39
	s_nop 0
	global_load_lds_dwordx4 v[224:225], off
	s_waitcnt vmcnt(8)
	s_waitcnt lgkmcnt(0)
	s_barrier
	s_waitcnt lgkmcnt(0)
	v_mfma_f32_16x16x32_bf16 v[68:71], v[182:185], v[150:153], v[68:71]
	v_mfma_f32_16x16x32_bf16 v[68:71], v[186:189], v[154:157], v[68:71]
	v_mfma_f32_16x16x32_bf16 v[64:67], v[190:193], v[150:153], v[64:67]
	v_mfma_f32_16x16x32_bf16 v[64:67], v[194:197], v[154:157], v[64:67]
	v_mfma_f32_16x16x32_bf16 v[48:51], v[208:211], v[150:153], v[48:51]
	v_mfma_f32_16x16x32_bf16 v[48:51], v[212:215], v[154:157], v[48:51]
	v_mfma_f32_16x16x32_bf16 v[40:43], v[216:219], v[150:153], v[40:43]
	v_mfma_f32_16x16x32_bf16 v[40:43], v[220:223], v[154:157], v[40:43]
	v_mfma_f32_16x16x32_bf16 v[60:63], v[182:185], v[158:161], v[60:63]
	v_mfma_f32_16x16x32_bf16 v[60:63], v[186:189], v[162:165], v[60:63]
	v_mfma_f32_16x16x32_bf16 v[56:59], v[190:193], v[158:161], v[56:59]
	v_mfma_f32_16x16x32_bf16 v[56:59], v[194:197], v[162:165], v[56:59]
	v_mfma_f32_16x16x32_bf16 v[32:35], v[208:211], v[158:161], v[32:35]
	v_mfma_f32_16x16x32_bf16 v[32:35], v[212:215], v[162:165], v[32:35]
	v_mfma_f32_16x16x32_bf16 v[24:27], v[216:219], v[158:161], v[24:27]
	v_mfma_f32_16x16x32_bf16 v[24:27], v[220:223], v[162:165], v[24:27]
	v_mfma_f32_16x16x32_bf16 v[52:55], v[182:185], v[166:169], v[52:55]
	v_mfma_f32_16x16x32_bf16 v[52:55], v[186:189], v[170:173], v[52:55]
	v_mfma_f32_16x16x32_bf16 v[44:47], v[190:193], v[166:169], v[44:47]
	v_mfma_f32_16x16x32_bf16 v[44:47], v[194:197], v[170:173], v[44:47]
	v_mfma_f32_16x16x32_bf16 v[20:23], v[208:211], v[166:169], v[20:23]
	v_mfma_f32_16x16x32_bf16 v[20:23], v[212:215], v[170:173], v[20:23]
	v_mfma_f32_16x16x32_bf16 v[16:19], v[216:219], v[166:169], v[16:19]
	v_mfma_f32_16x16x32_bf16 v[16:19], v[220:223], v[170:173], v[16:19]
	v_mfma_f32_16x16x32_bf16 v[36:39], v[182:185], v[174:177], v[36:39]
	v_mfma_f32_16x16x32_bf16 v[36:39], v[186:189], v[178:181], v[36:39]
	v_mfma_f32_16x16x32_bf16 v[28:31], v[190:193], v[174:177], v[28:31]
	v_mfma_f32_16x16x32_bf16 v[28:31], v[194:197], v[178:181], v[28:31]
	v_mfma_f32_16x16x32_bf16 v[12:15], v[208:211], v[174:177], v[12:15]
	v_mfma_f32_16x16x32_bf16 v[12:15], v[212:215], v[178:181], v[12:15]
	v_mfma_f32_16x16x32_bf16 v[8:11], v[216:219], v[174:177], v[8:11]
	v_mfma_f32_16x16x32_bf16 v[8:11], v[220:223], v[178:181], v[8:11]
	s_barrier
	s_add_i32 s58, 0, 0x18000
	s_add_i32 s59, 0, 0x1c000
	s_add_u32 s14, s14, 0x20000
	s_addc_u32 s15, s15, 0
	s_mov_b32 m0, s40
	v_add_u32_e32 v194, s58, v1
	v_add_u32_e32 v207, s59, v1
	v_lshl_add_u64 v[226:227], s[14:15], 0, v[140:141]
	ds_read_b128 v[150:153], v7 offset:32768
	ds_read_b128 v[154:157], v7 offset:33792
	ds_read_b128 v[158:161], v7 offset:34816
	ds_read_b128 v[162:165], v7 offset:35840
	ds_read_b128 v[166:169], v7 offset:36864
	ds_read_b128 v[170:173], v7 offset:37888
	ds_read_b128 v[174:177], v7 offset:38912
	ds_read_b128 v[178:181], v7 offset:39936
	ds_read_b128 v[182:185], v194
	ds_read_b128 v[186:189], v194 offset:1024
	ds_read_b128 v[190:193], v194 offset:2048
	ds_read_b128 v[194:197], v194 offset:3072
	ds_read_b128 v[208:211], v207
	ds_read_b128 v[212:215], v207 offset:1024
	ds_read_b128 v[216:219], v207 offset:2048
	ds_read_b128 v[220:223], v207 offset:3072
	global_load_lds_dwordx4 v[226:227], off
	v_lshl_add_u64 v[226:227], s[14:15], 0, v[138:139]
	s_mov_b32 m0, s41
	s_nop 0
	global_load_lds_dwordx4 v[226:227], off
	s_waitcnt vmcnt(8)
	s_waitcnt lgkmcnt(0)
	s_barrier
	s_waitcnt lgkmcnt(0)
	v_mfma_f32_16x16x32_bf16 v[132:135], v[182:185], v[150:153], v[132:135]
	v_mfma_f32_16x16x32_bf16 v[132:135], v[186:189], v[154:157], v[132:135]
	v_mfma_f32_16x16x32_bf16 v[128:131], v[190:193], v[150:153], v[128:131]
	v_mfma_f32_16x16x32_bf16 v[128:131], v[194:197], v[154:157], v[128:131]
	v_mfma_f32_16x16x32_bf16 v[112:115], v[208:211], v[150:153], v[112:115]
	v_mfma_f32_16x16x32_bf16 v[112:115], v[212:215], v[154:157], v[112:115]
	v_mfma_f32_16x16x32_bf16 v[104:107], v[216:219], v[150:153], v[104:107]
	v_mfma_f32_16x16x32_bf16 v[104:107], v[220:223], v[154:157], v[104:107]
	v_mfma_f32_16x16x32_bf16 v[124:127], v[182:185], v[158:161], v[124:127]
	v_mfma_f32_16x16x32_bf16 v[124:127], v[186:189], v[162:165], v[124:127]
	v_mfma_f32_16x16x32_bf16 v[120:123], v[190:193], v[158:161], v[120:123]
	v_mfma_f32_16x16x32_bf16 v[120:123], v[194:197], v[162:165], v[120:123]
	v_mfma_f32_16x16x32_bf16 v[96:99], v[208:211], v[158:161], v[96:99]
	v_mfma_f32_16x16x32_bf16 v[96:99], v[212:215], v[162:165], v[96:99]
	v_mfma_f32_16x16x32_bf16 v[88:91], v[216:219], v[158:161], v[88:91]
	v_mfma_f32_16x16x32_bf16 v[88:91], v[220:223], v[162:165], v[88:91]
	v_mfma_f32_16x16x32_bf16 v[116:119], v[182:185], v[166:169], v[116:119]
	v_mfma_f32_16x16x32_bf16 v[116:119], v[186:189], v[170:173], v[116:119]
	v_mfma_f32_16x16x32_bf16 v[108:111], v[190:193], v[166:169], v[108:111]
	v_mfma_f32_16x16x32_bf16 v[108:111], v[194:197], v[170:173], v[108:111]
	v_mfma_f32_16x16x32_bf16 v[84:87], v[208:211], v[166:169], v[84:87]
	v_mfma_f32_16x16x32_bf16 v[84:87], v[212:215], v[170:173], v[84:87]
	v_mfma_f32_16x16x32_bf16 v[80:83], v[216:219], v[166:169], v[80:83]
	v_mfma_f32_16x16x32_bf16 v[80:83], v[220:223], v[170:173], v[80:83]
	v_mfma_f32_16x16x32_bf16 v[100:103], v[182:185], v[174:177], v[100:103]
	v_mfma_f32_16x16x32_bf16 v[100:103], v[186:189], v[178:181], v[100:103]
	v_mfma_f32_16x16x32_bf16 v[92:95], v[190:193], v[174:177], v[92:95]
	v_mfma_f32_16x16x32_bf16 v[92:95], v[194:197], v[178:181], v[92:95]
	v_mfma_f32_16x16x32_bf16 v[76:79], v[208:211], v[174:177], v[76:79]
	v_mfma_f32_16x16x32_bf16 v[76:79], v[212:215], v[178:181], v[76:79]
	v_mfma_f32_16x16x32_bf16 v[72:75], v[216:219], v[174:177], v[72:75]
	v_mfma_f32_16x16x32_bf16 v[72:75], v[220:223], v[178:181], v[72:75]
	s_barrier
	s_add_i32 s14, s58, s35
	v_lshl_add_u64 v[136:137], v[136:137], 0, s[0:1]
	s_mov_b32 m0, s14
	ds_read_b128 v[150:153], v7 offset:49152
	ds_read_b128 v[154:157], v7 offset:50176
	ds_read_b128 v[158:161], v7 offset:51200
	ds_read_b128 v[162:165], v7 offset:52224
	ds_read_b128 v[166:169], v7 offset:53248
	ds_read_b128 v[170:173], v7 offset:54272
	ds_read_b128 v[174:177], v7 offset:55296
	ds_read_b128 v[178:181], v7 offset:56320
	global_load_lds_dwordx4 v[136:137], off
	s_add_i32 m0, s14, 0x2000
	s_add_u32 s12, s12, 0x20080
	v_lshl_add_u64 v[136:137], v[198:199], 0, s[0:1]
	s_addc_u32 s13, s13, 0
	s_add_i32 s14, s59, s35
	global_load_lds_dwordx4 v[136:137], off
	v_lshl_add_u64 v[136:137], s[12:13], 0, v[2:3]
	s_mov_b32 m0, s14
	s_nop 0
	global_load_lds_dwordx4 v[136:137], off
	v_lshl_add_u64 v[136:137], s[12:13], 0, v[4:5]
	s_add_i32 m0, s14, 0x2000
	s_nop 0
	global_load_lds_dwordx4 v[136:137], off
	v_lshl_add_u64 v[136:137], v[204:205], 0, s[0:1]
	s_mov_b32 m0, s49
	s_nop 0
	global_load_lds_dwordx4 v[136:137], off
	v_lshl_add_u64 v[136:137], v[224:225], 0, s[0:1]
	s_mov_b32 m0, s52
	s_nop 0
	global_load_lds_dwordx4 v[136:137], off
	s_waitcnt vmcnt(8)
	s_waitcnt lgkmcnt(0)
	s_barrier
	s_waitcnt lgkmcnt(0)
	v_mfma_f32_16x16x32_bf16 v[68:71], v[182:185], v[150:153], v[68:71]
	v_mfma_f32_16x16x32_bf16 v[68:71], v[186:189], v[154:157], v[68:71]
	v_mfma_f32_16x16x32_bf16 v[64:67], v[190:193], v[150:153], v[64:67]
	v_mfma_f32_16x16x32_bf16 v[64:67], v[194:197], v[154:157], v[64:67]
	v_mfma_f32_16x16x32_bf16 v[48:51], v[208:211], v[150:153], v[48:51]
	v_mfma_f32_16x16x32_bf16 v[48:51], v[212:215], v[154:157], v[48:51]
	v_mfma_f32_16x16x32_bf16 v[40:43], v[216:219], v[150:153], v[40:43]
	v_mfma_f32_16x16x32_bf16 v[40:43], v[220:223], v[154:157], v[40:43]
	v_mfma_f32_16x16x32_bf16 v[60:63], v[182:185], v[158:161], v[60:63]
	v_mfma_f32_16x16x32_bf16 v[60:63], v[186:189], v[162:165], v[60:63]
	v_mfma_f32_16x16x32_bf16 v[56:59], v[190:193], v[158:161], v[56:59]
	v_mfma_f32_16x16x32_bf16 v[56:59], v[194:197], v[162:165], v[56:59]
	v_mfma_f32_16x16x32_bf16 v[32:35], v[208:211], v[158:161], v[32:35]
	v_mfma_f32_16x16x32_bf16 v[32:35], v[212:215], v[162:165], v[32:35]
	v_mfma_f32_16x16x32_bf16 v[24:27], v[216:219], v[158:161], v[24:27]
	v_mfma_f32_16x16x32_bf16 v[24:27], v[220:223], v[162:165], v[24:27]
	v_mfma_f32_16x16x32_bf16 v[52:55], v[182:185], v[166:169], v[52:55]
	v_mfma_f32_16x16x32_bf16 v[52:55], v[186:189], v[170:173], v[52:55]
	v_mfma_f32_16x16x32_bf16 v[44:47], v[190:193], v[166:169], v[44:47]
	v_mfma_f32_16x16x32_bf16 v[44:47], v[194:197], v[170:173], v[44:47]
	v_mfma_f32_16x16x32_bf16 v[20:23], v[208:211], v[166:169], v[20:23]
	v_mfma_f32_16x16x32_bf16 v[20:23], v[212:215], v[170:173], v[20:23]
	v_mfma_f32_16x16x32_bf16 v[16:19], v[216:219], v[166:169], v[16:19]
	v_mfma_f32_16x16x32_bf16 v[16:19], v[220:223], v[170:173], v[16:19]
	v_mfma_f32_16x16x32_bf16 v[36:39], v[182:185], v[174:177], v[36:39]
	v_mfma_f32_16x16x32_bf16 v[36:39], v[186:189], v[178:181], v[36:39]
	v_mfma_f32_16x16x32_bf16 v[28:31], v[190:193], v[174:177], v[28:31]
	v_mfma_f32_16x16x32_bf16 v[28:31], v[194:197], v[178:181], v[28:31]
	v_mfma_f32_16x16x32_bf16 v[12:15], v[208:211], v[174:177], v[12:15]
	v_mfma_f32_16x16x32_bf16 v[12:15], v[212:215], v[178:181], v[12:15]
	v_mfma_f32_16x16x32_bf16 v[8:11], v[216:219], v[174:177], v[8:11]
	v_mfma_f32_16x16x32_bf16 v[8:11], v[220:223], v[178:181], v[8:11]
	s_barrier
	s_add_i32 s57, s57, 2
	s_add_u32 s42, s42, 0x100
	s_addc_u32 s43, s43, 0
	s_add_u32 s26, s26, 0x100
	s_addc_u32 s27, s27, 0
	s_cmp_gt_u32 s57, 5
	s_cbranch_scc0 .LBB0_620
	s_and_b64 vcc, exec, s[6:7]
	s_cbranch_vccz .LBB0_623
	s_barrier

.LBB0_986:
	s_add_u32 s12, s44, 0xfff80080
	s_addc_u32 s13, s45, -1
	s_cmp_eq_u32 s50, 28
	s_cselect_b32 s15, s18, s13
	s_cselect_b32 s14, s19, s12
	s_cselect_b32 s13, s17, s43
	s_cselect_b32 s12, s21, s33
	s_add_i32 s51, 0, 0x10000
	v_add_u32_e32 v2, s51, v7
	s_add_i32 s63, 0, 0x14000
	ds_read_b128 v[150:153], v155
	ds_read_b128 v[156:159], v155 offset:1024
	ds_read_b128 v[160:163], v155 offset:2048
	ds_read_b128 v[164:167], v155 offset:3072
	ds_read_b128 v[168:171], v155 offset:4096
	ds_read_b128 v[172:175], v155 offset:5120
	ds_read_b128 v[176:179], v155 offset:6144
	ds_read_b128 v[180:183], v155 offset:7168
	ds_read_b128 v[184:187], v2
	ds_read_b128 v[188:191], v2 offset:1024
	ds_read_b128 v[192:195], v2 offset:2048
	ds_read_b128 v[196:199], v2 offset:3072
	v_add_u32_e32 v2, s63, v7
	v_lshl_add_u64 v[224:225], s[44:45], 0, v[146:147]
	s_add_i32 m0, s39, 0xc000
	ds_read_b128 v[208:211], v2
	ds_read_b128 v[212:215], v2 offset:1024
	ds_read_b128 v[216:219], v2 offset:2048
	ds_read_b128 v[220:223], v2 offset:3072
	global_load_lds_dwordx4 v[224:225], off
	v_lshl_add_u64 v[224:225], s[44:45], 0, v[148:149]
	s_add_i32 m0, s39, 0xe000
	s_nop 0
	global_load_lds_dwordx4 v[224:225], off
	s_waitcnt vmcnt(8)
	s_waitcnt lgkmcnt(0)
	s_barrier
	s_waitcnt lgkmcnt(0)
	v_mfma_f32_16x16x32_bf16 v[132:135], v[184:187], v[150:153], v[132:135]
	v_mfma_f32_16x16x32_bf16 v[132:135], v[188:191], v[156:159], v[132:135]
	v_mfma_f32_16x16x32_bf16 v[128:131], v[192:195], v[150:153], v[128:131]
	v_mfma_f32_16x16x32_bf16 v[128:131], v[196:199], v[156:159], v[128:131]
	v_mfma_f32_16x16x32_bf16 v[124:127], v[208:211], v[150:153], v[124:127]
	v_mfma_f32_16x16x32_bf16 v[124:127], v[212:215], v[156:159], v[124:127]
	v_mfma_f32_16x16x32_bf16 v[120:123], v[216:219], v[150:153], v[120:123]
	v_mfma_f32_16x16x32_bf16 v[120:123], v[220:223], v[156:159], v[120:123]
	v_mfma_f32_16x16x32_bf16 v[116:119], v[184:187], v[160:163], v[116:119]
	v_mfma_f32_16x16x32_bf16 v[116:119], v[188:191], v[164:167], v[116:119]
	v_mfma_f32_16x16x32_bf16 v[112:115], v[192:195], v[160:163], v[112:115]
	v_mfma_f32_16x16x32_bf16 v[112:115], v[196:199], v[164:167], v[112:115]
	v_mfma_f32_16x16x32_bf16 v[108:111], v[208:211], v[160:163], v[108:111]
	v_mfma_f32_16x16x32_bf16 v[108:111], v[212:215], v[164:167], v[108:111]
	v_mfma_f32_16x16x32_bf16 v[104:107], v[216:219], v[160:163], v[104:107]
	v_mfma_f32_16x16x32_bf16 v[104:107], v[220:223], v[164:167], v[104:107]
	v_mfma_f32_16x16x32_bf16 v[100:103], v[184:187], v[168:171], v[100:103]
	v_mfma_f32_16x16x32_bf16 v[100:103], v[188:191], v[172:175], v[100:103]
	v_mfma_f32_16x16x32_bf16 v[96:99], v[192:195], v[168:171], v[96:99]
	v_mfma_f32_16x16x32_bf16 v[96:99], v[196:199], v[172:175], v[96:99]
	v_mfma_f32_16x16x32_bf16 v[92:95], v[208:211], v[168:171], v[92:95]
	v_mfma_f32_16x16x32_bf16 v[92:95], v[212:215], v[172:175], v[92:95]
	v_mfma_f32_16x16x32_bf16 v[88:91], v[216:219], v[168:171], v[88:91]
	v_mfma_f32_16x16x32_bf16 v[88:91], v[220:223], v[172:175], v[88:91]
	v_mfma_f32_16x16x32_bf16 v[84:87], v[184:187], v[176:179], v[84:87]
	v_mfma_f32_16x16x32_bf16 v[84:87], v[188:191], v[180:183], v[84:87]
	v_mfma_f32_16x16x32_bf16 v[80:83], v[192:195], v[176:179], v[80:83]
	v_mfma_f32_16x16x32_bf16 v[80:83], v[196:199], v[180:183], v[80:83]
	v_mfma_f32_16x16x32_bf16 v[76:79], v[208:211], v[176:179], v[76:79]
	v_mfma_f32_16x16x32_bf16 v[76:79], v[212:215], v[180:183], v[76:79]
	v_mfma_f32_16x16x32_bf16 v[72:75], v[216:219], v[176:179], v[72:75]
	v_mfma_f32_16x16x32_bf16 v[72:75], v[220:223], v[180:183], v[72:75]
	s_barrier
	s_add_i32 s51, s51, s38
	v_lshl_add_u64 v[224:225], s[12:13], 0, v[138:139]
	s_mov_b32 m0, s51
	ds_read_b128 v[150:153], v155 offset:16384
	ds_read_b128 v[156:159], v155 offset:17408
	ds_read_b128 v[160:163], v155 offset:18432
	ds_read_b128 v[164:167], v155 offset:19456
	ds_read_b128 v[168:171], v155 offset:20480
	ds_read_b128 v[172:175], v155 offset:21504
	ds_read_b128 v[176:179], v155 offset:22528
	ds_read_b128 v[180:183], v155 offset:23552
	global_load_lds_dwordx4 v[224:225], off
	s_add_i32 m0, s51, 0x2000
	s_add_u32 s64, s12, 0x80000
	v_lshl_add_u64 v[226:227], s[12:13], 0, v[4:5]
	s_addc_u32 s65, s13, 0
	s_add_i32 s51, s63, s38
	global_load_lds_dwordx4 v[226:227], off
	v_lshl_add_u64 v[228:229], s[64:65], 0, v[138:139]
	s_mov_b32 m0, s51
	v_lshl_add_u64 v[230:231], s[14:15], 0, v[136:137]
	global_load_lds_dwordx4 v[228:229], off
	v_lshl_add_u64 v[228:229], s[64:65], 0, v[4:5]
	s_add_i32 m0, s51, 0x2000
	s_nop 0
	global_load_lds_dwordx4 v[228:229], off
	v_lshl_add_u64 v[228:229], s[14:15], 0, v[140:141]
	s_mov_b32 m0, s39
	s_nop 0
	global_load_lds_dwordx4 v[228:229], off
	s_mov_b32 m0, s40
	s_nop 0
	global_load_lds_dwordx4 v[230:231], off
	s_waitcnt vmcnt(8)
	s_waitcnt lgkmcnt(0)
	s_barrier
	s_waitcnt lgkmcnt(0)
	v_mfma_f32_16x16x32_bf16 v[68:71], v[184:187], v[150:153], v[68:71]
	v_mfma_f32_16x16x32_bf16 v[68:71], v[188:191], v[156:159], v[68:71]
	v_mfma_f32_16x16x32_bf16 v[64:67], v[192:195], v[150:153], v[64:67]
	v_mfma_f32_16x16x32_bf16 v[64:67], v[196:199], v[156:159], v[64:67]
	v_mfma_f32_16x16x32_bf16 v[60:63], v[208:211], v[150:153], v[60:63]
	v_mfma_f32_16x16x32_bf16 v[60:63], v[212:215], v[156:159], v[60:63]
	v_mfma_f32_16x16x32_bf16 v[56:59], v[216:219], v[150:153], v[56:59]
	v_mfma_f32_16x16x32_bf16 v[56:59], v[220:223], v[156:159], v[56:59]
	v_mfma_f32_16x16x32_bf16 v[52:55], v[184:187], v[160:163], v[52:55]
	v_mfma_f32_16x16x32_bf16 v[52:55], v[188:191], v[164:167], v[52:55]
	v_mfma_f32_16x16x32_bf16 v[48:51], v[192:195], v[160:163], v[48:51]
	v_mfma_f32_16x16x32_bf16 v[48:51], v[196:199], v[164:167], v[48:51]
	v_mfma_f32_16x16x32_bf16 v[44:47], v[208:211], v[160:163], v[44:47]
	v_mfma_f32_16x16x32_bf16 v[44:47], v[212:215], v[164:167], v[44:47]
	v_mfma_f32_16x16x32_bf16 v[40:43], v[216:219], v[160:163], v[40:43]
	v_mfma_f32_16x16x32_bf16 v[40:43], v[220:223], v[164:167], v[40:43]
	v_mfma_f32_16x16x32_bf16 v[36:39], v[184:187], v[168:171], v[36:39]
	v_mfma_f32_16x16x32_bf16 v[36:39], v[188:191], v[172:175], v[36:39]
	v_mfma_f32_16x16x32_bf16 v[32:35], v[192:195], v[168:171], v[32:35]
	v_mfma_f32_16x16x32_bf16 v[32:35], v[196:199], v[172:175], v[32:35]
	v_mfma_f32_16x16x32_bf16 v[28:31], v[208:211], v[168:171], v[28:31]
	v_mfma_f32_16x16x32_bf16 v[28:31], v[212:215], v[172:175], v[28:31]
	v_mfma_f32_16x16x32_bf16 v[24:27], v[216:219], v[168:171], v[24:27]
	v_mfma_f32_16x16x32_bf16 v[24:27], v[220:223], v[172:175], v[24:27]
	v_mfma_f32_16x16x32_bf16 v[20:23], v[184:187], v[176:179], v[20:23]
	v_mfma_f32_16x16x32_bf16 v[20:23], v[188:191], v[180:183], v[20:23]
	v_mfma_f32_16x16x32_bf16 v[16:19], v[192:195], v[176:179], v[16:19]
	v_mfma_f32_16x16x32_bf16 v[16:19], v[196:199], v[180:183], v[16:19]
	v_mfma_f32_16x16x32_bf16 v[12:15], v[208:211], v[176:179], v[12:15]
	v_mfma_f32_16x16x32_bf16 v[12:15], v[212:215], v[180:183], v[12:15]
	v_mfma_f32_16x16x32_bf16 v[8:11], v[216:219], v[176:179], v[8:11]
	v_mfma_f32_16x16x32_bf16 v[8:11], v[220:223], v[180:183], v[8:11]
	s_barrier
	s_add_i32 s51, 0, 0x18000
	s_add_i32 s63, 0, 0x1c000
	s_add_u32 s14, s14, 0x80000
	v_add_u32_e32 v2, s51, v7
	s_addc_u32 s15, s15, 0
	s_mov_b32 m0, s41
	ds_read_b128 v[150:153], v155 offset:32768
	ds_read_b128 v[156:159], v155 offset:33792
	ds_read_b128 v[160:163], v155 offset:34816
	ds_read_b128 v[164:167], v155 offset:35840
	ds_read_b128 v[168:171], v155 offset:36864
	ds_read_b128 v[172:175], v155 offset:37888
	ds_read_b128 v[176:179], v155 offset:38912
	ds_read_b128 v[180:183], v155 offset:39936
	ds_read_b128 v[184:187], v2
	ds_read_b128 v[188:191], v2 offset:1024
	ds_read_b128 v[192:195], v2 offset:2048
	ds_read_b128 v[196:199], v2 offset:3072
	v_add_u32_e32 v2, s63, v7
	v_lshl_add_u64 v[232:233], s[14:15], 0, v[140:141]
	ds_read_b128 v[208:211], v2
	ds_read_b128 v[212:215], v2 offset:1024
	ds_read_b128 v[216:219], v2 offset:2048
	ds_read_b128 v[220:223], v2 offset:3072
	global_load_lds_dwordx4 v[232:233], off
	v_lshl_add_u64 v[232:233], s[14:15], 0, v[136:137]
	s_mov_b32 m0, s47
	s_nop 0
	global_load_lds_dwordx4 v[232:233], off
	s_waitcnt vmcnt(8)
	s_waitcnt lgkmcnt(0)
	s_barrier
	s_waitcnt lgkmcnt(0)
	v_mfma_f32_16x16x32_bf16 v[132:135], v[184:187], v[150:153], v[132:135]
	v_mfma_f32_16x16x32_bf16 v[132:135], v[188:191], v[156:159], v[132:135]
	v_mfma_f32_16x16x32_bf16 v[128:131], v[192:195], v[150:153], v[128:131]
	v_mfma_f32_16x16x32_bf16 v[128:131], v[196:199], v[156:159], v[128:131]
	v_mfma_f32_16x16x32_bf16 v[124:127], v[208:211], v[150:153], v[124:127]
	v_mfma_f32_16x16x32_bf16 v[124:127], v[212:215], v[156:159], v[124:127]
	v_mfma_f32_16x16x32_bf16 v[120:123], v[216:219], v[150:153], v[120:123]
	v_mfma_f32_16x16x32_bf16 v[120:123], v[220:223], v[156:159], v[120:123]
	v_mfma_f32_16x16x32_bf16 v[116:119], v[184:187], v[160:163], v[116:119]
	v_mfma_f32_16x16x32_bf16 v[116:119], v[188:191], v[164:167], v[116:119]
	v_mfma_f32_16x16x32_bf16 v[112:115], v[192:195], v[160:163], v[112:115]
	v_mfma_f32_16x16x32_bf16 v[112:115], v[196:199], v[164:167], v[112:115]
	v_mfma_f32_16x16x32_bf16 v[108:111], v[208:211], v[160:163], v[108:111]
	v_mfma_f32_16x16x32_bf16 v[108:111], v[212:215], v[164:167], v[108:111]
	v_mfma_f32_16x16x32_bf16 v[104:107], v[216:219], v[160:163], v[104:107]
	v_mfma_f32_16x16x32_bf16 v[104:107], v[220:223], v[164:167], v[104:107]
	v_mfma_f32_16x16x32_bf16 v[100:103], v[184:187], v[168:171], v[100:103]
	v_mfma_f32_16x16x32_bf16 v[100:103], v[188:191], v[172:175], v[100:103]
	v_mfma_f32_16x16x32_bf16 v[96:99], v[192:195], v[168:171], v[96:99]
	v_mfma_f32_16x16x32_bf16 v[96:99], v[196:199], v[172:175], v[96:99]
	v_mfma_f32_16x16x32_bf16 v[92:95], v[208:211], v[168:171], v[92:95]
	v_mfma_f32_16x16x32_bf16 v[92:95], v[212:215], v[172:175], v[92:95]
	v_mfma_f32_16x16x32_bf16 v[88:91], v[216:219], v[168:171], v[88:91]
	v_mfma_f32_16x16x32_bf16 v[88:91], v[220:223], v[172:175], v[88:91]
	v_mfma_f32_16x16x32_bf16 v[84:87], v[184:187], v[176:179], v[84:87]
	v_mfma_f32_16x16x32_bf16 v[84:87], v[188:191], v[180:183], v[84:87]
	v_mfma_f32_16x16x32_bf16 v[80:83], v[192:195], v[176:179], v[80:83]
	v_mfma_f32_16x16x32_bf16 v[80:83], v[196:199], v[180:183], v[80:83]
	v_mfma_f32_16x16x32_bf16 v[76:79], v[208:211], v[176:179], v[76:79]
	v_mfma_f32_16x16x32_bf16 v[76:79], v[212:215], v[180:183], v[76:79]
	v_mfma_f32_16x16x32_bf16 v[72:75], v[216:219], v[176:179], v[72:75]
	v_mfma_f32_16x16x32_bf16 v[72:75], v[220:223], v[180:183], v[72:75]
	s_barrier
	s_add_i32 s14, s51, s38
	v_lshl_add_u64 v[224:225], v[224:225], 0, s[0:1]
	s_mov_b32 m0, s14
	ds_read_b128 v[150:153], v155 offset:49152
	ds_read_b128 v[156:159], v155 offset:50176
	ds_read_b128 v[160:163], v155 offset:51200
	ds_read_b128 v[164:167], v155 offset:52224
	ds_read_b128 v[168:171], v155 offset:53248
	ds_read_b128 v[172:175], v155 offset:54272
	ds_read_b128 v[176:179], v155 offset:55296
	ds_read_b128 v[180:183], v155 offset:56320
	global_load_lds_dwordx4 v[224:225], off
	s_add_i32 m0, s14, 0x2000
	s_add_u32 s12, s12, 0x80080
	v_lshl_add_u64 v[224:225], v[226:227], 0, s[0:1]
	s_addc_u32 s13, s13, 0
	s_add_i32 s14, s63, s38
	global_load_lds_dwordx4 v[224:225], off
	v_lshl_add_u64 v[224:225], s[12:13], 0, v[138:139]
	s_mov_b32 m0, s14
	s_nop 0
	global_load_lds_dwordx4 v[224:225], off
	v_lshl_add_u64 v[224:225], s[12:13], 0, v[4:5]
	s_add_i32 m0, s14, 0x2000
	s_nop 0
	global_load_lds_dwordx4 v[224:225], off
	v_lshl_add_u64 v[224:225], v[228:229], 0, s[0:1]
	s_mov_b32 m0, s60
	s_nop 0
	global_load_lds_dwordx4 v[224:225], off
	v_lshl_add_u64 v[224:225], v[230:231], 0, s[0:1]
	s_mov_b32 m0, s61
	s_nop 0
	global_load_lds_dwordx4 v[224:225], off
	s_waitcnt vmcnt(8)
	s_waitcnt lgkmcnt(0)
	s_barrier
	s_waitcnt lgkmcnt(0)
	v_mfma_f32_16x16x32_bf16 v[68:71], v[184:187], v[150:153], v[68:71]
	v_mfma_f32_16x16x32_bf16 v[68:71], v[188:191], v[156:159], v[68:71]
	v_mfma_f32_16x16x32_bf16 v[64:67], v[192:195], v[150:153], v[64:67]
	v_mfma_f32_16x16x32_bf16 v[64:67], v[196:199], v[156:159], v[64:67]
	v_mfma_f32_16x16x32_bf16 v[60:63], v[208:211], v[150:153], v[60:63]
	v_mfma_f32_16x16x32_bf16 v[60:63], v[212:215], v[156:159], v[60:63]
	v_mfma_f32_16x16x32_bf16 v[56:59], v[216:219], v[150:153], v[56:59]
	v_mfma_f32_16x16x32_bf16 v[56:59], v[220:223], v[156:159], v[56:59]
	v_mfma_f32_16x16x32_bf16 v[52:55], v[184:187], v[160:163], v[52:55]
	v_mfma_f32_16x16x32_bf16 v[52:55], v[188:191], v[164:167], v[52:55]
	v_mfma_f32_16x16x32_bf16 v[48:51], v[192:195], v[160:163], v[48:51]
	v_mfma_f32_16x16x32_bf16 v[48:51], v[196:199], v[164:167], v[48:51]
	v_mfma_f32_16x16x32_bf16 v[44:47], v[208:211], v[160:163], v[44:47]
	v_mfma_f32_16x16x32_bf16 v[44:47], v[212:215], v[164:167], v[44:47]
	v_mfma_f32_16x16x32_bf16 v[40:43], v[216:219], v[160:163], v[40:43]
	v_mfma_f32_16x16x32_bf16 v[40:43], v[220:223], v[164:167], v[40:43]
	v_mfma_f32_16x16x32_bf16 v[36:39], v[184:187], v[168:171], v[36:39]
	v_mfma_f32_16x16x32_bf16 v[36:39], v[188:191], v[172:175], v[36:39]
	v_mfma_f32_16x16x32_bf16 v[32:35], v[192:195], v[168:171], v[32:35]
	v_mfma_f32_16x16x32_bf16 v[32:35], v[196:199], v[172:175], v[32:35]
	v_mfma_f32_16x16x32_bf16 v[28:31], v[208:211], v[168:171], v[28:31]
	v_mfma_f32_16x16x32_bf16 v[28:31], v[212:215], v[172:175], v[28:31]
	v_mfma_f32_16x16x32_bf16 v[24:27], v[216:219], v[168:171], v[24:27]
	v_mfma_f32_16x16x32_bf16 v[24:27], v[220:223], v[172:175], v[24:27]
	v_mfma_f32_16x16x32_bf16 v[20:23], v[184:187], v[176:179], v[20:23]
	v_mfma_f32_16x16x32_bf16 v[20:23], v[188:191], v[180:183], v[20:23]
	v_mfma_f32_16x16x32_bf16 v[16:19], v[192:195], v[176:179], v[16:19]
	v_mfma_f32_16x16x32_bf16 v[16:19], v[196:199], v[180:183], v[16:19]
	v_mfma_f32_16x16x32_bf16 v[12:15], v[208:211], v[176:179], v[12:15]
	v_mfma_f32_16x16x32_bf16 v[12:15], v[212:215], v[180:183], v[12:15]
	v_mfma_f32_16x16x32_bf16 v[8:11], v[216:219], v[176:179], v[8:11]
	v_mfma_f32_16x16x32_bf16 v[8:11], v[220:223], v[180:183], v[8:11]
	s_barrier
	s_add_i32 s50, s50, 2
	s_add_u32 s44, s44, 0x100
	s_addc_u32 s45, s45, 0
	s_add_u32 s33, s33, 0x100
	s_addc_u32 s43, s43, 0
	s_cmp_gt_u32 s50, 29
	s_cbranch_scc0 .LBB0_986
	s_and_b64 vcc, exec, s[10:11]
	s_cbranch_vccz .LBB0_1031
	s_barrier
	s_cmp_gt_i32 s35, 15
	s_mov_b64 s[12:13], -1
	s_cbranch_scc1 .LBB0_1032

.LBB0_1482:
	s_add_i32 s26, s12, 2
	s_cmp_eq_u32 s57, s12
	s_cselect_b32 s13, s43, s51
	s_cselect_b32 s12, s42, s50
	s_cselect_b32 s65, s45, s15
	s_cselect_b32 s64, s44, s14
	s_add_i32 s27, 0, 0x10000
	s_movk_i32 s66, 0xff80
	v_add_u32_e32 v121, s27, v7
	s_add_i32 s63, 0, 0x14000
	v_lshl_add_u64 v[178:179], s[50:51], 0, v[108:109]
	s_mov_b32 s67, -1
	ds_read_b128 v[110:113], v119
	ds_read_b128 v[114:117], v119 offset:1024
	ds_read_b128 v[122:125], v119 offset:2048
	ds_read_b128 v[126:129], v119 offset:3072
	ds_read_b128 v[130:133], v119 offset:4096
	ds_read_b128 v[134:137], v119 offset:5120
	ds_read_b128 v[138:141], v119 offset:6144
	ds_read_b128 v[142:145], v119 offset:7168
	ds_read_b128 v[146:149], v121
	ds_read_b128 v[150:153], v121 offset:1024
	ds_read_b128 v[154:157], v121 offset:2048
	ds_read_b128 v[158:161], v121 offset:3072
	v_add_u32_e32 v121, s63, v7
	v_lshl_add_u64 v[178:179], v[178:179], 0, s[66:67]
	s_add_i32 m0, s39, 0xc000
	ds_read_b128 v[162:165], v121
	ds_read_b128 v[166:169], v121 offset:1024
	ds_read_b128 v[170:173], v121 offset:2048
	ds_read_b128 v[174:177], v121 offset:3072
	global_load_lds_dwordx4 v[178:179], off
	s_waitcnt vmcnt(7)
	s_waitcnt lgkmcnt(0)
	s_barrier
	s_waitcnt lgkmcnt(0)
	v_mfma_f32_16x16x32_bf16 v[100:103], v[146:149], v[110:113], v[100:103]
	v_mfma_f32_16x16x32_bf16 v[100:103], v[150:153], v[114:117], v[100:103]
	v_mfma_f32_16x16x32_bf16 v[96:99], v[154:157], v[110:113], v[96:99]
	v_mfma_f32_16x16x32_bf16 v[96:99], v[158:161], v[114:117], v[96:99]
	v_mfma_f32_16x16x32_bf16 v[88:91], v[162:165], v[110:113], v[88:91]
	v_mfma_f32_16x16x32_bf16 v[88:91], v[166:169], v[114:117], v[88:91]
	v_mfma_f32_16x16x32_bf16 v[84:87], v[170:173], v[110:113], v[84:87]
	v_mfma_f32_16x16x32_bf16 v[84:87], v[174:177], v[114:117], v[84:87]
	v_mfma_f32_16x16x32_bf16 v[92:95], v[146:149], v[122:125], v[92:95]
	v_mfma_f32_16x16x32_bf16 v[92:95], v[150:153], v[126:129], v[92:95]
	v_mfma_f32_16x16x32_bf16 v[80:83], v[154:157], v[122:125], v[80:83]
	v_mfma_f32_16x16x32_bf16 v[80:83], v[158:161], v[126:129], v[80:83]
	v_mfma_f32_16x16x32_bf16 v[76:79], v[162:165], v[122:125], v[76:79]
	v_mfma_f32_16x16x32_bf16 v[76:79], v[166:169], v[126:129], v[76:79]
	v_mfma_f32_16x16x32_bf16 v[68:71], v[170:173], v[122:125], v[68:71]
	v_mfma_f32_16x16x32_bf16 v[68:71], v[174:177], v[126:129], v[68:71]
	v_mfma_f32_16x16x32_bf16 v[72:75], v[146:149], v[130:133], v[72:75]
	v_mfma_f32_16x16x32_bf16 v[72:75], v[150:153], v[134:137], v[72:75]
	v_mfma_f32_16x16x32_bf16 v[64:67], v[154:157], v[130:133], v[64:67]
	v_mfma_f32_16x16x32_bf16 v[64:67], v[158:161], v[134:137], v[64:67]
	v_mfma_f32_16x16x32_bf16 v[60:63], v[162:165], v[130:133], v[60:63]
	v_mfma_f32_16x16x32_bf16 v[60:63], v[166:169], v[134:137], v[60:63]
	v_mfma_f32_16x16x32_bf16 v[52:55], v[170:173], v[130:133], v[52:55]
	v_mfma_f32_16x16x32_bf16 v[52:55], v[174:177], v[134:137], v[52:55]
	v_mfma_f32_16x16x32_bf16 v[56:59], v[146:149], v[138:141], v[56:59]
	v_mfma_f32_16x16x32_bf16 v[56:59], v[150:153], v[142:145], v[56:59]
	v_mfma_f32_16x16x32_bf16 v[48:51], v[154:157], v[138:141], v[48:51]
	v_mfma_f32_16x16x32_bf16 v[48:51], v[158:161], v[142:145], v[48:51]
	v_mfma_f32_16x16x32_bf16 v[44:47], v[162:165], v[138:141], v[44:47]
	v_mfma_f32_16x16x32_bf16 v[44:47], v[166:169], v[142:145], v[44:47]
	v_mfma_f32_16x16x32_bf16 v[40:43], v[170:173], v[138:141], v[40:43]
	v_mfma_f32_16x16x32_bf16 v[40:43], v[174:177], v[142:145], v[40:43]
	s_barrier
	s_add_i32 s27, s27, s22
	v_lshl_add_u64 v[178:179], s[64:65], 0, v[2:3]
	s_mov_b32 m0, s27
	ds_read_b128 v[110:113], v120 offset:16384
	ds_read_b128 v[114:117], v120 offset:17408
	ds_read_b128 v[122:125], v120 offset:18432
	ds_read_b128 v[126:129], v120 offset:19456
	global_load_lds_dwordx4 v[178:179], off
	s_add_i32 m0, s27, 0x2000
	v_lshl_add_u64 v[180:181], s[64:65], 0, v[4:5]
	s_add_u32 s64, s64, s90
	s_addc_u32 s65, s65, 0
	s_add_i32 s27, s63, s22
	global_load_lds_dwordx4 v[180:181], off
	v_lshl_add_u64 v[182:183], s[64:65], 0, v[2:3]
	s_mov_b32 m0, s27
	v_lshl_add_u64 v[184:185], s[64:65], 0, v[4:5]
	global_load_lds_dwordx4 v[182:183], off
	s_add_i32 m0, s27, 0x2000
	v_lshl_add_u64 v[186:187], s[12:13], 0, v[106:107]
	global_load_lds_dwordx4 v[184:185], off
	s_mov_b32 m0, s39
	v_lshl_add_u64 v[188:189], s[12:13], 0, v[104:105]
	global_load_lds_dwordx4 v[186:187], off
	s_mov_b32 m0, s40
	s_nop 0
	global_load_lds_dwordx4 v[188:189], off
	s_waitcnt vmcnt(7)
	s_waitcnt lgkmcnt(0)
	s_barrier
	s_waitcnt lgkmcnt(0)
	v_mfma_f32_16x16x32_bf16 v[36:39], v[146:149], v[110:113], v[36:39]
	v_mfma_f32_16x16x32_bf16 v[36:39], v[150:153], v[114:117], v[36:39]
	v_mfma_f32_16x16x32_bf16 v[32:35], v[154:157], v[110:113], v[32:35]
	v_mfma_f32_16x16x32_bf16 v[32:35], v[158:161], v[114:117], v[32:35]
	v_mfma_f32_16x16x32_bf16 v[28:31], v[162:165], v[110:113], v[28:31]
	v_mfma_f32_16x16x32_bf16 v[28:31], v[166:169], v[114:117], v[28:31]
	v_mfma_f32_16x16x32_bf16 v[24:27], v[170:173], v[110:113], v[24:27]
	v_mfma_f32_16x16x32_bf16 v[24:27], v[174:177], v[114:117], v[24:27]
	v_mfma_f32_16x16x32_bf16 v[20:23], v[146:149], v[122:125], v[20:23]
	v_mfma_f32_16x16x32_bf16 v[20:23], v[150:153], v[126:129], v[20:23]
	v_mfma_f32_16x16x32_bf16 v[16:19], v[154:157], v[122:125], v[16:19]
	v_mfma_f32_16x16x32_bf16 v[16:19], v[158:161], v[126:129], v[16:19]
	v_mfma_f32_16x16x32_bf16 v[12:15], v[162:165], v[122:125], v[12:15]
	v_mfma_f32_16x16x32_bf16 v[12:15], v[166:169], v[126:129], v[12:15]
	v_mfma_f32_16x16x32_bf16 v[8:11], v[170:173], v[122:125], v[8:11]
	v_mfma_f32_16x16x32_bf16 v[8:11], v[174:177], v[126:129], v[8:11]
	s_barrier
	s_add_i32 s27, 0, 0x18000
	s_add_i32 s63, 0, 0x1c000
	s_add_u32 s12, s12, s90
	v_add_u32_e32 v121, s27, v7
	s_addc_u32 s13, s13, 0
	ds_read_b128 v[110:113], v119 offset:32768
	ds_read_b128 v[114:117], v119 offset:33792
	ds_read_b128 v[122:125], v119 offset:34816
	ds_read_b128 v[126:129], v119 offset:35840
	ds_read_b128 v[130:133], v119 offset:36864
	ds_read_b128 v[134:137], v119 offset:37888
	ds_read_b128 v[138:141], v119 offset:38912
	ds_read_b128 v[142:145], v119 offset:39936
	ds_read_b128 v[146:149], v121
	ds_read_b128 v[150:153], v121 offset:1024
	ds_read_b128 v[154:157], v121 offset:2048
	ds_read_b128 v[158:161], v121 offset:3072
	v_add_u32_e32 v121, s63, v7
	v_lshl_add_u64 v[190:191], s[12:13], 0, v[106:107]
	s_mov_b32 m0, s41
	ds_read_b128 v[162:165], v121
	ds_read_b128 v[166:169], v121 offset:1024
	ds_read_b128 v[170:173], v121 offset:2048
	ds_read_b128 v[174:177], v121 offset:3072
	global_load_lds_dwordx4 v[190:191], off
	s_waitcnt vmcnt(7)
	s_waitcnt lgkmcnt(0)
	s_barrier
	s_waitcnt lgkmcnt(0)
	v_mfma_f32_16x16x32_bf16 v[100:103], v[146:149], v[110:113], v[100:103]
	v_mfma_f32_16x16x32_bf16 v[100:103], v[150:153], v[114:117], v[100:103]
	v_mfma_f32_16x16x32_bf16 v[96:99], v[154:157], v[110:113], v[96:99]
	v_mfma_f32_16x16x32_bf16 v[96:99], v[158:161], v[114:117], v[96:99]
	v_mfma_f32_16x16x32_bf16 v[88:91], v[162:165], v[110:113], v[88:91]
	v_mfma_f32_16x16x32_bf16 v[88:91], v[166:169], v[114:117], v[88:91]
	v_mfma_f32_16x16x32_bf16 v[84:87], v[170:173], v[110:113], v[84:87]
	v_mfma_f32_16x16x32_bf16 v[84:87], v[174:177], v[114:117], v[84:87]
	v_mfma_f32_16x16x32_bf16 v[92:95], v[146:149], v[122:125], v[92:95]
	v_mfma_f32_16x16x32_bf16 v[92:95], v[150:153], v[126:129], v[92:95]
	v_mfma_f32_16x16x32_bf16 v[80:83], v[154:157], v[122:125], v[80:83]
	v_mfma_f32_16x16x32_bf16 v[80:83], v[158:161], v[126:129], v[80:83]
	v_mfma_f32_16x16x32_bf16 v[76:79], v[162:165], v[122:125], v[76:79]
	v_mfma_f32_16x16x32_bf16 v[76:79], v[166:169], v[126:129], v[76:79]
	v_mfma_f32_16x16x32_bf16 v[68:71], v[170:173], v[122:125], v[68:71]
	v_mfma_f32_16x16x32_bf16 v[68:71], v[174:177], v[126:129], v[68:71]
	v_mfma_f32_16x16x32_bf16 v[72:75], v[146:149], v[130:133], v[72:75]
	v_mfma_f32_16x16x32_bf16 v[72:75], v[150:153], v[134:137], v[72:75]
	v_mfma_f32_16x16x32_bf16 v[64:67], v[154:157], v[130:133], v[64:67]
	v_mfma_f32_16x16x32_bf16 v[64:67], v[158:161], v[134:137], v[64:67]
	v_mfma_f32_16x16x32_bf16 v[60:63], v[162:165], v[130:133], v[60:63]
	v_mfma_f32_16x16x32_bf16 v[60:63], v[166:169], v[134:137], v[60:63]
	v_mfma_f32_16x16x32_bf16 v[52:55], v[170:173], v[130:133], v[52:55]
	v_mfma_f32_16x16x32_bf16 v[52:55], v[174:177], v[134:137], v[52:55]
	v_mfma_f32_16x16x32_bf16 v[56:59], v[146:149], v[138:141], v[56:59]
	v_mfma_f32_16x16x32_bf16 v[56:59], v[150:153], v[142:145], v[56:59]
	v_mfma_f32_16x16x32_bf16 v[48:51], v[154:157], v[138:141], v[48:51]
	v_mfma_f32_16x16x32_bf16 v[48:51], v[158:161], v[142:145], v[48:51]
	v_mfma_f32_16x16x32_bf16 v[44:47], v[162:165], v[138:141], v[44:47]
	v_mfma_f32_16x16x32_bf16 v[44:47], v[166:169], v[142:145], v[44:47]
	v_mfma_f32_16x16x32_bf16 v[40:43], v[170:173], v[138:141], v[40:43]
	v_mfma_f32_16x16x32_bf16 v[40:43], v[174:177], v[142:145], v[40:43]
	s_barrier
	s_add_i32 s12, s27, s22
	v_lshl_add_u64 v[130:131], v[178:179], 0, s[0:1]
	s_mov_b32 m0, s12
	ds_read_b128 v[110:113], v120 offset:49152
	ds_read_b128 v[114:117], v120 offset:50176
	ds_read_b128 v[122:125], v120 offset:51200
	ds_read_b128 v[126:129], v120 offset:52224
	global_load_lds_dwordx4 v[130:131], off
	v_lshl_add_u64 v[130:131], v[180:181], 0, s[0:1]
	s_add_i32 m0, s12, 0x2000
	s_add_i32 s12, s63, s22
	global_load_lds_dwordx4 v[130:131], off
	v_lshl_add_u64 v[130:131], v[182:183], 0, s[0:1]
	s_mov_b32 m0, s12
	s_nop 0
	global_load_lds_dwordx4 v[130:131], off
	v_lshl_add_u64 v[130:131], v[184:185], 0, s[0:1]
	s_add_i32 m0, s12, 0x2000
	s_nop 0
	global_load_lds_dwordx4 v[130:131], off
	v_lshl_add_u64 v[130:131], v[186:187], 0, s[0:1]
	s_mov_b32 m0, s53
	s_nop 0
	global_load_lds_dwordx4 v[130:131], off
	v_lshl_add_u64 v[130:131], v[188:189], 0, s[0:1]
	s_mov_b32 m0, s54
	s_nop 0
	global_load_lds_dwordx4 v[130:131], off
	s_waitcnt vmcnt(7)
	s_waitcnt lgkmcnt(0)
	s_barrier
	s_waitcnt lgkmcnt(0)
	v_mfma_f32_16x16x32_bf16 v[36:39], v[146:149], v[110:113], v[36:39]
	v_mfma_f32_16x16x32_bf16 v[36:39], v[150:153], v[114:117], v[36:39]
	v_mfma_f32_16x16x32_bf16 v[32:35], v[154:157], v[110:113], v[32:35]
	v_mfma_f32_16x16x32_bf16 v[32:35], v[158:161], v[114:117], v[32:35]
	v_mfma_f32_16x16x32_bf16 v[28:31], v[162:165], v[110:113], v[28:31]
	v_mfma_f32_16x16x32_bf16 v[28:31], v[166:169], v[114:117], v[28:31]
	v_mfma_f32_16x16x32_bf16 v[24:27], v[170:173], v[110:113], v[24:27]
	v_mfma_f32_16x16x32_bf16 v[24:27], v[174:177], v[114:117], v[24:27]
	v_mfma_f32_16x16x32_bf16 v[20:23], v[146:149], v[122:125], v[20:23]
	v_mfma_f32_16x16x32_bf16 v[20:23], v[150:153], v[126:129], v[20:23]
	v_mfma_f32_16x16x32_bf16 v[16:19], v[154:157], v[122:125], v[16:19]
	v_mfma_f32_16x16x32_bf16 v[16:19], v[158:161], v[126:129], v[16:19]
	v_mfma_f32_16x16x32_bf16 v[12:15], v[162:165], v[122:125], v[12:15]
	v_mfma_f32_16x16x32_bf16 v[12:15], v[166:169], v[126:129], v[12:15]
	v_mfma_f32_16x16x32_bf16 v[8:11], v[170:173], v[122:125], v[8:11]
	v_mfma_f32_16x16x32_bf16 v[8:11], v[174:177], v[126:129], v[8:11]
	s_barrier
	s_add_u32 s50, s50, 0x100
	s_addc_u32 s51, s51, 0
	s_add_u32 s14, s14, 0x100
	s_addc_u32 s15, s15, 0
	s_cmp_ge_u32 s26, s55
	s_mov_b32 s12, s26
	s_cbranch_scc0 .LBB0_1482
	s_and_b64 vcc, exec, s[36:37]
	s_cbranch_vccz .LBB0_1485
	s_barrier
